# scan: producer stages (nk_t, r_{t-1}) interleaved so the consumer gets dot-product and y partials from the same 4 packed FMAs (2 fewer VALU + 2 fewer slots per step)
# speedup vs baseline: 1.0767x; 1.0101x over previous
; #define LAS __attribute__((address_space(3)))
; #define RW_LDS_WAIT(X) asm volatile("s_waitcnt lgkmcnt(0)" : "+v"(nk##X), "+v"(dd##X), "+v"(bb##X), "+v"(kp##X), "+v"(rr##X), "+v"(vv##X) :: "memory")
; DI void rwkv_scan_phase(int wv, const Params& P, LAS unsigned char* lds) {
;     ...
;             for (int ck = 0; ck < nck; ++ck) { const int buf = ck & 1;
;                 const LAS float* sb = stg + buf * RW_T * 5 * 64 + 4 * cg; const LAS float* vb = vst + buf * RW_T * 8 + rloc; LAS float* yb = ybuf + buf * RW_T * 128 + wave * 64 + lane;
;                 const unsigned sba = (unsigned)(size_t)sb, vba = (unsigned)(size_t)vb;
;                 f32x4 nkA, ddA, bbA, kpA, rrA, nkB, ddB, bbB, kpB, rrB; float vvA, vvB;
;     ...
;                 f32x2 yacc = (f32x2){0.f, 0.f};
;                 unsigned sbt = sba, vbt = vba; LAS float* ybt = yb;
;                 RW_LDS_LOAD(A, 0); RW_LDS_WAIT(A);
; #pragma unroll 1
;                 for (int tt = 0; tt < RW_T; tt += 16) { sbt = sba + (unsigned)tt * 1280u; vbt = vba + (unsigned)tt * 32u; ybt = yb + tt * 128;
;                     RW_LDS_LOAD(B, 1); RW_STEP(A, 0); RW_LDS_WAIT(B);
;                     RW_LDS_LOAD(A, 2); RW_STEP(B, 1); RW_LDS_WAIT(A);
;                     RW_LDS_LOAD(B, 3); RW_STEP(A, 2); RW_LDS_WAIT(B);
;                     RW_LDS_LOAD(A, 4); RW_STEP(B, 3); RW_LDS_WAIT(A);
;                     RW_LDS_LOAD(B, 5); RW_STEP(A, 4); RW_LDS_WAIT(B);
;                     RW_LDS_LOAD(A, 6); RW_STEP(B, 5); RW_LDS_WAIT(A);
;                     RW_LDS_LOAD(B, 7); RW_STEP(A, 6); RW_LDS_WAIT(B);
;                     RW_LDS_LOAD(A, 8); RW_STEP(B, 7); RW_LDS_WAIT(A);
;                     RW_LDS_LOAD(B, 9); RW_STEP(A, 8); RW_LDS_WAIT(B);
;                     RW_LDS_LOAD(A, 10); RW_STEP(B, 9); RW_LDS_WAIT(A);
;                     RW_LDS_LOAD(B, 11); RW_STEP(A, 10); RW_LDS_WAIT(B);
;                     RW_LDS_LOAD(A, 12); RW_STEP(B, 11); RW_LDS_WAIT(A);
;                     RW_LDS_LOAD(B, 13); RW_STEP(A, 12); RW_LDS_WAIT(B);
;                     RW_LDS_LOAD(A, 14); RW_STEP(B, 13); RW_LDS_WAIT(A);
;                     RW_LDS_LOAD(B, 15); RW_STEP(A, 14); RW_LDS_WAIT(B);
;                     RW_LDS_LOAD(A, 16); RW_STEP(B, 15); RW_LDS_WAIT(A);
;                 }
.Lscan_chunk:
	s_lshl_b32 s40, s47, 5
	s_and_b32 s40, s40, 32
	s_mul_i32 s41, s40, 0x500
	v_add_u32_e32 v74, s41, v45
	v_add_u32_e32 v73, v74, v45
	v_lshl_add_u32 v75, s40, 5, v63
	v_lshl_add_u32 v72, s40, 9, v66
	s_lshl_b32 s41, s40, 3
	s_add_i32 s41, s41, 0x1c800
	v_add_u32_e32 v40, s41, v45
	ds_read_b128 v[0:3], v73
	ds_read_b128 v[16:19], v73 offset:16
	ds_read_b32 v42, v75
	ds_read_b128 v[4:7], v74 offset:512
	ds_read_b128 v[8:11], v74 offset:768
	ds_read_b128 v[12:15], v74 offset:1024
	ds_read_b128 v[20:23], v73 offset:1280
	ds_read_b128 v[36:39], v73 offset:1296
	ds_read_b32 v62, v75 offset:32
	ds_read_b128 v[24:27], v74 offset:1792
	ds_read_b128 v[28:31], v74 offset:2048
	ds_read_b128 v[32:35], v74 offset:2304
	s_waitcnt lgkmcnt(6)
	v_pk_mul_f32 v[0:1], v[58:59], v[0:1] op_sel_hi:[0,1]
	ds_read_b128 v[46:49], v73 offset:2560
	v_pk_fma_f32 v[0:1], v[58:59], v[2:3], v[0:1] op_sel:[1,0,0] op_sel_hi:[1,1,1]
	ds_read_b128 v[76:79], v73 offset:2576
	v_pk_fma_f32 v[0:1], v[60:61], v[16:17], v[0:1] op_sel_hi:[0,1,1]
	ds_read_b32 v44, v75 offset:64
	v_pk_fma_f32 v[0:1], v[60:61], v[18:19], v[0:1] op_sel:[1,0,0] op_sel_hi:[1,1,1]
	v_pk_mul_f32 v[12:13], v[12:13], v[42:43] op_sel_hi:[1,0]
	v_pk_mul_f32 v[14:15], v[14:15], v[42:43] op_sel_hi:[1,0]
	v_add_f32_dpp v0, v0, v0 quad_perm:[1,0,3,2] row_mask:0xf bank_mask:0xf bound_ctrl:1
	v_pk_fma_f32 v[12:13], v[58:59], v[4:5], v[12:13]
	v_pk_fma_f32 v[14:15], v[60:61], v[6:7], v[14:15]
	v_add_f32_dpp v0, v0, v0 quad_perm:[2,3,0,1] row_mask:0xf bank_mask:0xf bound_ctrl:1
	ds_read_b128 v[50:53], v74 offset:3072
	ds_read_b128 v[54:57], v74 offset:3328
	v_add_f32_dpp v0, v0, v0 row_half_mirror row_mask:0xf bank_mask:0xf bound_ctrl:1
	ds_read_b128 v[68:71], v74 offset:3584
	s_nop 0
	v_add_f32_dpp v0, v0, v0 row_mirror row_mask:0xf bank_mask:0xf bound_ctrl:1
	v_pk_fma_f32 v[58:59], v[8:9], v[0:1], v[12:13] op_sel_hi:[1,0,1]
	v_pk_fma_f32 v[60:61], v[10:11], v[0:1], v[14:15] op_sel_hi:[1,0,1]
	s_waitcnt lgkmcnt(6)
	v_pk_mul_f32 v[20:21], v[58:59], v[20:21] op_sel_hi:[0,1]
	ds_read_b128 v[0:3], v73 offset:3840
	v_pk_fma_f32 v[20:21], v[58:59], v[22:23], v[20:21] op_sel:[1,0,0] op_sel_hi:[1,1,1]
	ds_read_b128 v[16:19], v73 offset:3856
	v_pk_fma_f32 v[20:21], v[60:61], v[36:37], v[20:21] op_sel_hi:[0,1,1]
	ds_read_b32 v42, v75 offset:96
	v_pk_fma_f32 v[20:21], v[60:61], v[38:39], v[20:21] op_sel:[1,0,0] op_sel_hi:[1,1,1]
	v_pk_mul_f32 v[32:33], v[32:33], v[62:63] op_sel_hi:[1,0]
	v_pk_mul_f32 v[34:35], v[34:35], v[62:63] op_sel_hi:[1,0]
	v_add_f32_dpp v20, v20, v20 quad_perm:[1,0,3,2] row_mask:0xf bank_mask:0xf bound_ctrl:1
	v_pk_fma_f32 v[32:33], v[58:59], v[24:25], v[32:33]
	v_pk_fma_f32 v[34:35], v[60:61], v[26:27], v[34:35]
	v_add_f32_dpp v20, v20, v20 quad_perm:[2,3,0,1] row_mask:0xf bank_mask:0xf bound_ctrl:1
	ds_read_b128 v[4:7], v74 offset:4352
	ds_read_b128 v[8:11], v74 offset:4608
	v_add_f32_dpp v20, v20, v20 row_half_mirror row_mask:0xf bank_mask:0xf bound_ctrl:1
	ds_read_b128 v[12:15], v74 offset:4864
	ds_write_b32 v72, v21
	v_add_f32_dpp v20, v20, v20 row_mirror row_mask:0xf bank_mask:0xf bound_ctrl:1
	v_pk_fma_f32 v[58:59], v[28:29], v[20:21], v[32:33] op_sel_hi:[1,0,1]
	v_pk_fma_f32 v[60:61], v[30:31], v[20:21], v[34:35] op_sel_hi:[1,0,1]
	s_waitcnt lgkmcnt(7)
	v_pk_mul_f32 v[46:47], v[58:59], v[46:47] op_sel_hi:[0,1]
	ds_read_b128 v[20:23], v73 offset:5120
	v_pk_fma_f32 v[46:47], v[58:59], v[48:49], v[46:47] op_sel:[1,0,0] op_sel_hi:[1,1,1]
	ds_read_b128 v[36:39], v73 offset:5136
	v_pk_fma_f32 v[46:47], v[60:61], v[76:77], v[46:47] op_sel_hi:[0,1,1]
	ds_read_b32 v62, v75 offset:128
	v_pk_fma_f32 v[46:47], v[60:61], v[78:79], v[46:47] op_sel:[1,0,0] op_sel_hi:[1,1,1]
	v_pk_mul_f32 v[68:69], v[68:69], v[44:45] op_sel_hi:[1,0]
	v_pk_mul_f32 v[70:71], v[70:71], v[44:45] op_sel_hi:[1,0]
	v_add_f32_dpp v46, v46, v46 quad_perm:[1,0,3,2] row_mask:0xf bank_mask:0xf bound_ctrl:1
	v_pk_fma_f32 v[68:69], v[58:59], v[50:51], v[68:69]
	v_pk_fma_f32 v[70:71], v[60:61], v[52:53], v[70:71]
	v_add_f32_dpp v46, v46, v46 quad_perm:[2,3,0,1] row_mask:0xf bank_mask:0xf bound_ctrl:1
	ds_read_b128 v[24:27], v74 offset:5632
	ds_read_b128 v[28:31], v74 offset:5888
	v_add_f32_dpp v46, v46, v46 row_half_mirror row_mask:0xf bank_mask:0xf bound_ctrl:1
	ds_read_b128 v[32:35], v74 offset:6144
	ds_write_b32 v72, v47 offset:512
	v_add_f32_dpp v46, v46, v46 row_mirror row_mask:0xf bank_mask:0xf bound_ctrl:1
	v_pk_fma_f32 v[58:59], v[54:55], v[46:47], v[68:69] op_sel_hi:[1,0,1]
	v_pk_fma_f32 v[60:61], v[56:57], v[46:47], v[70:71] op_sel_hi:[1,0,1]
	s_waitcnt lgkmcnt(8)
	v_pk_mul_f32 v[0:1], v[58:59], v[0:1] op_sel_hi:[0,1]
	ds_read_b128 v[46:49], v73 offset:6400
	v_pk_fma_f32 v[0:1], v[58:59], v[2:3], v[0:1] op_sel:[1,0,0] op_sel_hi:[1,1,1]
	ds_read_b128 v[76:79], v73 offset:6416
	v_pk_fma_f32 v[0:1], v[60:61], v[16:17], v[0:1] op_sel_hi:[0,1,1]
	ds_read_b32 v44, v75 offset:160
	v_pk_fma_f32 v[0:1], v[60:61], v[18:19], v[0:1] op_sel:[1,0,0] op_sel_hi:[1,1,1]
	v_pk_mul_f32 v[12:13], v[12:13], v[42:43] op_sel_hi:[1,0]
	v_pk_mul_f32 v[14:15], v[14:15], v[42:43] op_sel_hi:[1,0]
	v_add_f32_dpp v0, v0, v0 quad_perm:[1,0,3,2] row_mask:0xf bank_mask:0xf bound_ctrl:1
	v_pk_fma_f32 v[12:13], v[58:59], v[4:5], v[12:13]
	v_pk_fma_f32 v[14:15], v[60:61], v[6:7], v[14:15]
	v_add_f32_dpp v0, v0, v0 quad_perm:[2,3,0,1] row_mask:0xf bank_mask:0xf bound_ctrl:1
	ds_read_b128 v[50:53], v74 offset:6912
	ds_read_b128 v[54:57], v74 offset:7168
	v_add_f32_dpp v0, v0, v0 row_half_mirror row_mask:0xf bank_mask:0xf bound_ctrl:1
	ds_read_b128 v[68:71], v74 offset:7424
	ds_write_b32 v72, v1 offset:1024
	v_add_f32_dpp v0, v0, v0 row_mirror row_mask:0xf bank_mask:0xf bound_ctrl:1
	v_pk_fma_f32 v[58:59], v[8:9], v[0:1], v[12:13] op_sel_hi:[1,0,1]
	v_pk_fma_f32 v[60:61], v[10:11], v[0:1], v[14:15] op_sel_hi:[1,0,1]
	s_waitcnt lgkmcnt(8)
; #define LAS __attribute__((address_space(3)))
; #define RW_LDS_WAIT(X) asm volatile("s_waitcnt lgkmcnt(0)" : "+v"(nk##X), "+v"(dd##X), "+v"(bb##X), "+v"(kp##X), "+v"(rr##X), "+v"(vv##X) :: "memory")
; DI void rwkv_scan_phase(int wv, const Params& P, LAS unsigned char* lds) {
;     ...
;                 f32x2 yacc = (f32x2){0.f, 0.f};
;                 unsigned sbt = sba, vbt = vba; LAS float* ybt = yb;
;                 RW_LDS_LOAD(A, 0); RW_LDS_WAIT(A);
; #pragma unroll 1
;                 for (int tt = 0; tt < RW_T; tt += 16) { sbt = sba + (unsigned)tt * 1280u; vbt = vba + (unsigned)tt * 32u; ybt = yb + tt * 128;
;                     RW_LDS_LOAD(B, 1); RW_STEP(A, 0); RW_LDS_WAIT(B);
;                     RW_LDS_LOAD(A, 2); RW_STEP(B, 1); RW_LDS_WAIT(A);
;                     RW_LDS_LOAD(B, 3); RW_STEP(A, 2); RW_LDS_WAIT(B);
;                     RW_LDS_LOAD(A, 4); RW_STEP(B, 3); RW_LDS_WAIT(A);
;                     RW_LDS_LOAD(B, 5); RW_STEP(A, 4); RW_LDS_WAIT(B);
;                     RW_LDS_LOAD(A, 6); RW_STEP(B, 5); RW_LDS_WAIT(A);
;                     RW_LDS_LOAD(B, 7); RW_STEP(A, 6); RW_LDS_WAIT(B);
;                     RW_LDS_LOAD(A, 8); RW_STEP(B, 7); RW_LDS_WAIT(A);
;                     RW_LDS_LOAD(B, 9); RW_STEP(A, 8); RW_LDS_WAIT(B);
;                     RW_LDS_LOAD(A, 10); RW_STEP(B, 9); RW_LDS_WAIT(A);
;                     RW_LDS_LOAD(B, 11); RW_STEP(A, 10); RW_LDS_WAIT(B);
;                     RW_LDS_LOAD(A, 12); RW_STEP(B, 11); RW_LDS_WAIT(A);
;                     RW_LDS_LOAD(B, 13); RW_STEP(A, 12); RW_LDS_WAIT(B);
;                     RW_LDS_LOAD(A, 14); RW_STEP(B, 13); RW_LDS_WAIT(A);
;                     RW_LDS_LOAD(B, 15); RW_STEP(A, 14); RW_LDS_WAIT(B);
;                     RW_LDS_LOAD(A, 16); RW_STEP(B, 15); RW_LDS_WAIT(A);
;                 }
	v_pk_mul_f32 v[20:21], v[58:59], v[20:21] op_sel_hi:[0,1]
	ds_read_b128 v[0:3], v73 offset:7680
	v_pk_fma_f32 v[20:21], v[58:59], v[22:23], v[20:21] op_sel:[1,0,0] op_sel_hi:[1,1,1]
	ds_read_b128 v[16:19], v73 offset:7696
	v_pk_fma_f32 v[20:21], v[60:61], v[36:37], v[20:21] op_sel_hi:[0,1,1]
	ds_read_b32 v42, v75 offset:192
	v_pk_fma_f32 v[20:21], v[60:61], v[38:39], v[20:21] op_sel:[1,0,0] op_sel_hi:[1,1,1]
	v_pk_mul_f32 v[32:33], v[32:33], v[62:63] op_sel_hi:[1,0]
	v_pk_mul_f32 v[34:35], v[34:35], v[62:63] op_sel_hi:[1,0]
	v_add_f32_dpp v20, v20, v20 quad_perm:[1,0,3,2] row_mask:0xf bank_mask:0xf bound_ctrl:1
	v_pk_fma_f32 v[32:33], v[58:59], v[24:25], v[32:33]
	v_pk_fma_f32 v[34:35], v[60:61], v[26:27], v[34:35]
	v_add_f32_dpp v20, v20, v20 quad_perm:[2,3,0,1] row_mask:0xf bank_mask:0xf bound_ctrl:1
	ds_read_b128 v[4:7], v74 offset:8192
	ds_read_b128 v[8:11], v74 offset:8448
	v_add_f32_dpp v20, v20, v20 row_half_mirror row_mask:0xf bank_mask:0xf bound_ctrl:1
	ds_read_b128 v[12:15], v74 offset:8704
	ds_write_b32 v72, v21 offset:1536
	v_add_f32_dpp v20, v20, v20 row_mirror row_mask:0xf bank_mask:0xf bound_ctrl:1
	v_pk_fma_f32 v[58:59], v[28:29], v[20:21], v[32:33] op_sel_hi:[1,0,1]
	v_pk_fma_f32 v[60:61], v[30:31], v[20:21], v[34:35] op_sel_hi:[1,0,1]
	s_waitcnt lgkmcnt(8)
	v_pk_mul_f32 v[46:47], v[58:59], v[46:47] op_sel_hi:[0,1]
	ds_read_b128 v[20:23], v73 offset:8960
	v_pk_fma_f32 v[46:47], v[58:59], v[48:49], v[46:47] op_sel:[1,0,0] op_sel_hi:[1,1,1]
	ds_read_b128 v[36:39], v73 offset:8976
	v_pk_fma_f32 v[46:47], v[60:61], v[76:77], v[46:47] op_sel_hi:[0,1,1]
	ds_read_b32 v62, v75 offset:224
	v_pk_fma_f32 v[46:47], v[60:61], v[78:79], v[46:47] op_sel:[1,0,0] op_sel_hi:[1,1,1]
	v_pk_mul_f32 v[68:69], v[68:69], v[44:45] op_sel_hi:[1,0]
	v_pk_mul_f32 v[70:71], v[70:71], v[44:45] op_sel_hi:[1,0]
	v_add_f32_dpp v46, v46, v46 quad_perm:[1,0,3,2] row_mask:0xf bank_mask:0xf bound_ctrl:1
	v_pk_fma_f32 v[68:69], v[58:59], v[50:51], v[68:69]
	v_pk_fma_f32 v[70:71], v[60:61], v[52:53], v[70:71]
	v_add_f32_dpp v46, v46, v46 quad_perm:[2,3,0,1] row_mask:0xf bank_mask:0xf bound_ctrl:1
	ds_read_b128 v[24:27], v74 offset:9472
	ds_read_b128 v[28:31], v74 offset:9728
	v_add_f32_dpp v46, v46, v46 row_half_mirror row_mask:0xf bank_mask:0xf bound_ctrl:1
	ds_read_b128 v[32:35], v74 offset:9984
	ds_write_b32 v72, v47 offset:2048
	v_add_f32_dpp v46, v46, v46 row_mirror row_mask:0xf bank_mask:0xf bound_ctrl:1
	v_pk_fma_f32 v[58:59], v[54:55], v[46:47], v[68:69] op_sel_hi:[1,0,1]
	v_pk_fma_f32 v[60:61], v[56:57], v[46:47], v[70:71] op_sel_hi:[1,0,1]
	s_waitcnt lgkmcnt(8)
	v_pk_mul_f32 v[0:1], v[58:59], v[0:1] op_sel_hi:[0,1]
	ds_read_b128 v[46:49], v73 offset:10240
	v_pk_fma_f32 v[0:1], v[58:59], v[2:3], v[0:1] op_sel:[1,0,0] op_sel_hi:[1,1,1]
	ds_read_b128 v[76:79], v73 offset:10256
	v_pk_fma_f32 v[0:1], v[60:61], v[16:17], v[0:1] op_sel_hi:[0,1,1]
	ds_read_b32 v44, v75 offset:256
	v_pk_fma_f32 v[0:1], v[60:61], v[18:19], v[0:1] op_sel:[1,0,0] op_sel_hi:[1,1,1]
	v_pk_mul_f32 v[12:13], v[12:13], v[42:43] op_sel_hi:[1,0]
	v_pk_mul_f32 v[14:15], v[14:15], v[42:43] op_sel_hi:[1,0]
	v_add_f32_dpp v0, v0, v0 quad_perm:[1,0,3,2] row_mask:0xf bank_mask:0xf bound_ctrl:1
	v_pk_fma_f32 v[12:13], v[58:59], v[4:5], v[12:13]
	v_pk_fma_f32 v[14:15], v[60:61], v[6:7], v[14:15]
	v_add_f32_dpp v0, v0, v0 quad_perm:[2,3,0,1] row_mask:0xf bank_mask:0xf bound_ctrl:1
	ds_read_b128 v[50:53], v74 offset:10752
	ds_read_b128 v[54:57], v74 offset:11008
	v_add_f32_dpp v0, v0, v0 row_half_mirror row_mask:0xf bank_mask:0xf bound_ctrl:1
	ds_read_b128 v[68:71], v74 offset:11264
	ds_write_b32 v72, v1 offset:2560
	v_add_f32_dpp v0, v0, v0 row_mirror row_mask:0xf bank_mask:0xf bound_ctrl:1
	v_pk_fma_f32 v[58:59], v[8:9], v[0:1], v[12:13] op_sel_hi:[1,0,1]
	v_pk_fma_f32 v[60:61], v[10:11], v[0:1], v[14:15] op_sel_hi:[1,0,1]
	s_waitcnt lgkmcnt(8)
	v_pk_mul_f32 v[20:21], v[58:59], v[20:21] op_sel_hi:[0,1]
	ds_read_b128 v[0:3], v73 offset:11520
	v_pk_fma_f32 v[20:21], v[58:59], v[22:23], v[20:21] op_sel:[1,0,0] op_sel_hi:[1,1,1]
	ds_read_b128 v[16:19], v73 offset:11536
	v_pk_fma_f32 v[20:21], v[60:61], v[36:37], v[20:21] op_sel_hi:[0,1,1]
	ds_read_b32 v42, v75 offset:288
	v_pk_fma_f32 v[20:21], v[60:61], v[38:39], v[20:21] op_sel:[1,0,0] op_sel_hi:[1,1,1]
	v_pk_mul_f32 v[32:33], v[32:33], v[62:63] op_sel_hi:[1,0]
	v_pk_mul_f32 v[34:35], v[34:35], v[62:63] op_sel_hi:[1,0]
	v_add_f32_dpp v20, v20, v20 quad_perm:[1,0,3,2] row_mask:0xf bank_mask:0xf bound_ctrl:1
	v_pk_fma_f32 v[32:33], v[58:59], v[24:25], v[32:33]
	v_pk_fma_f32 v[34:35], v[60:61], v[26:27], v[34:35]
	v_add_f32_dpp v20, v20, v20 quad_perm:[2,3,0,1] row_mask:0xf bank_mask:0xf bound_ctrl:1
	ds_read_b128 v[4:7], v74 offset:12032
	ds_read_b128 v[8:11], v74 offset:12288
	v_add_f32_dpp v20, v20, v20 row_half_mirror row_mask:0xf bank_mask:0xf bound_ctrl:1
	ds_read_b128 v[12:15], v74 offset:12544
	ds_write_b32 v72, v21 offset:3072
	v_add_f32_dpp v20, v20, v20 row_mirror row_mask:0xf bank_mask:0xf bound_ctrl:1
	v_pk_fma_f32 v[58:59], v[28:29], v[20:21], v[32:33] op_sel_hi:[1,0,1]
	v_pk_fma_f32 v[60:61], v[30:31], v[20:21], v[34:35] op_sel_hi:[1,0,1]
	s_waitcnt lgkmcnt(8)
; #define LAS __attribute__((address_space(3)))
; #define RW_LDS_WAIT(X) asm volatile("s_waitcnt lgkmcnt(0)" : "+v"(nk##X), "+v"(dd##X), "+v"(bb##X), "+v"(kp##X), "+v"(rr##X), "+v"(vv##X) :: "memory")
; DI void rwkv_scan_phase(int wv, const Params& P, LAS unsigned char* lds) {
;     ...
;                 f32x2 yacc = (f32x2){0.f, 0.f};
;                 unsigned sbt = sba, vbt = vba; LAS float* ybt = yb;
;                 RW_LDS_LOAD(A, 0); RW_LDS_WAIT(A);
; #pragma unroll 1
;                 for (int tt = 0; tt < RW_T; tt += 16) { sbt = sba + (unsigned)tt * 1280u; vbt = vba + (unsigned)tt * 32u; ybt = yb + tt * 128;
;                     RW_LDS_LOAD(B, 1); RW_STEP(A, 0); RW_LDS_WAIT(B);
;                     RW_LDS_LOAD(A, 2); RW_STEP(B, 1); RW_LDS_WAIT(A);
;                     RW_LDS_LOAD(B, 3); RW_STEP(A, 2); RW_LDS_WAIT(B);
;                     RW_LDS_LOAD(A, 4); RW_STEP(B, 3); RW_LDS_WAIT(A);
;                     RW_LDS_LOAD(B, 5); RW_STEP(A, 4); RW_LDS_WAIT(B);
;                     RW_LDS_LOAD(A, 6); RW_STEP(B, 5); RW_LDS_WAIT(A);
;                     RW_LDS_LOAD(B, 7); RW_STEP(A, 6); RW_LDS_WAIT(B);
;                     RW_LDS_LOAD(A, 8); RW_STEP(B, 7); RW_LDS_WAIT(A);
;                     RW_LDS_LOAD(B, 9); RW_STEP(A, 8); RW_LDS_WAIT(B);
;                     RW_LDS_LOAD(A, 10); RW_STEP(B, 9); RW_LDS_WAIT(A);
;                     RW_LDS_LOAD(B, 11); RW_STEP(A, 10); RW_LDS_WAIT(B);
;                     RW_LDS_LOAD(A, 12); RW_STEP(B, 11); RW_LDS_WAIT(A);
;                     RW_LDS_LOAD(B, 13); RW_STEP(A, 12); RW_LDS_WAIT(B);
;                     RW_LDS_LOAD(A, 14); RW_STEP(B, 13); RW_LDS_WAIT(A);
;                     RW_LDS_LOAD(B, 15); RW_STEP(A, 14); RW_LDS_WAIT(B);
;                     RW_LDS_LOAD(A, 16); RW_STEP(B, 15); RW_LDS_WAIT(A);
;                 }
	v_pk_mul_f32 v[46:47], v[58:59], v[46:47] op_sel_hi:[0,1]
	ds_read_b128 v[20:23], v73 offset:12800
	v_pk_fma_f32 v[46:47], v[58:59], v[48:49], v[46:47] op_sel:[1,0,0] op_sel_hi:[1,1,1]
	ds_read_b128 v[36:39], v73 offset:12816
	v_pk_fma_f32 v[46:47], v[60:61], v[76:77], v[46:47] op_sel_hi:[0,1,1]
	ds_read_b32 v62, v75 offset:320
	v_pk_fma_f32 v[46:47], v[60:61], v[78:79], v[46:47] op_sel:[1,0,0] op_sel_hi:[1,1,1]
	v_pk_mul_f32 v[68:69], v[68:69], v[44:45] op_sel_hi:[1,0]
	v_pk_mul_f32 v[70:71], v[70:71], v[44:45] op_sel_hi:[1,0]
	v_add_f32_dpp v46, v46, v46 quad_perm:[1,0,3,2] row_mask:0xf bank_mask:0xf bound_ctrl:1
	v_pk_fma_f32 v[68:69], v[58:59], v[50:51], v[68:69]
	v_pk_fma_f32 v[70:71], v[60:61], v[52:53], v[70:71]
	v_add_f32_dpp v46, v46, v46 quad_perm:[2,3,0,1] row_mask:0xf bank_mask:0xf bound_ctrl:1
	ds_read_b128 v[24:27], v74 offset:13312
	ds_read_b128 v[28:31], v74 offset:13568
	v_add_f32_dpp v46, v46, v46 row_half_mirror row_mask:0xf bank_mask:0xf bound_ctrl:1
	ds_read_b128 v[32:35], v74 offset:13824
	ds_write_b32 v72, v47 offset:3584
	v_add_f32_dpp v46, v46, v46 row_mirror row_mask:0xf bank_mask:0xf bound_ctrl:1
	v_pk_fma_f32 v[58:59], v[54:55], v[46:47], v[68:69] op_sel_hi:[1,0,1]
	v_pk_fma_f32 v[60:61], v[56:57], v[46:47], v[70:71] op_sel_hi:[1,0,1]
	s_waitcnt lgkmcnt(8)
	v_pk_mul_f32 v[0:1], v[58:59], v[0:1] op_sel_hi:[0,1]
	ds_read_b128 v[46:49], v73 offset:14080
	v_pk_fma_f32 v[0:1], v[58:59], v[2:3], v[0:1] op_sel:[1,0,0] op_sel_hi:[1,1,1]
	ds_read_b128 v[76:79], v73 offset:14096
	v_pk_fma_f32 v[0:1], v[60:61], v[16:17], v[0:1] op_sel_hi:[0,1,1]
	ds_read_b32 v44, v75 offset:352
	v_pk_fma_f32 v[0:1], v[60:61], v[18:19], v[0:1] op_sel:[1,0,0] op_sel_hi:[1,1,1]
	v_pk_mul_f32 v[12:13], v[12:13], v[42:43] op_sel_hi:[1,0]
	v_pk_mul_f32 v[14:15], v[14:15], v[42:43] op_sel_hi:[1,0]
	v_add_f32_dpp v0, v0, v0 quad_perm:[1,0,3,2] row_mask:0xf bank_mask:0xf bound_ctrl:1
	v_pk_fma_f32 v[12:13], v[58:59], v[4:5], v[12:13]
	v_pk_fma_f32 v[14:15], v[60:61], v[6:7], v[14:15]
	v_add_f32_dpp v0, v0, v0 quad_perm:[2,3,0,1] row_mask:0xf bank_mask:0xf bound_ctrl:1
	ds_read_b128 v[50:53], v74 offset:14592
	ds_read_b128 v[54:57], v74 offset:14848
	v_add_f32_dpp v0, v0, v0 row_half_mirror row_mask:0xf bank_mask:0xf bound_ctrl:1
	ds_read_b128 v[68:71], v74 offset:15104
	ds_write_b32 v72, v1 offset:4096
	v_add_f32_dpp v0, v0, v0 row_mirror row_mask:0xf bank_mask:0xf bound_ctrl:1
	v_pk_fma_f32 v[58:59], v[8:9], v[0:1], v[12:13] op_sel_hi:[1,0,1]
	v_pk_fma_f32 v[60:61], v[10:11], v[0:1], v[14:15] op_sel_hi:[1,0,1]
	s_waitcnt lgkmcnt(8)
	v_pk_mul_f32 v[20:21], v[58:59], v[20:21] op_sel_hi:[0,1]
	ds_read_b128 v[0:3], v73 offset:15360
	v_pk_fma_f32 v[20:21], v[58:59], v[22:23], v[20:21] op_sel:[1,0,0] op_sel_hi:[1,1,1]
	ds_read_b128 v[16:19], v73 offset:15376
	v_pk_fma_f32 v[20:21], v[60:61], v[36:37], v[20:21] op_sel_hi:[0,1,1]
	ds_read_b32 v42, v75 offset:384
	v_pk_fma_f32 v[20:21], v[60:61], v[38:39], v[20:21] op_sel:[1,0,0] op_sel_hi:[1,1,1]
	v_pk_mul_f32 v[32:33], v[32:33], v[62:63] op_sel_hi:[1,0]
	v_pk_mul_f32 v[34:35], v[34:35], v[62:63] op_sel_hi:[1,0]
	v_add_f32_dpp v20, v20, v20 quad_perm:[1,0,3,2] row_mask:0xf bank_mask:0xf bound_ctrl:1
	v_pk_fma_f32 v[32:33], v[58:59], v[24:25], v[32:33]
	v_pk_fma_f32 v[34:35], v[60:61], v[26:27], v[34:35]
	v_add_f32_dpp v20, v20, v20 quad_perm:[2,3,0,1] row_mask:0xf bank_mask:0xf bound_ctrl:1
	ds_read_b128 v[4:7], v74 offset:15872
	ds_read_b128 v[8:11], v74 offset:16128
	v_add_f32_dpp v20, v20, v20 row_half_mirror row_mask:0xf bank_mask:0xf bound_ctrl:1
	ds_read_b128 v[12:15], v74 offset:16384
	ds_write_b32 v72, v21 offset:4608
	v_add_f32_dpp v20, v20, v20 row_mirror row_mask:0xf bank_mask:0xf bound_ctrl:1
	v_pk_fma_f32 v[58:59], v[28:29], v[20:21], v[32:33] op_sel_hi:[1,0,1]
	v_pk_fma_f32 v[60:61], v[30:31], v[20:21], v[34:35] op_sel_hi:[1,0,1]
	s_waitcnt lgkmcnt(8)
	v_pk_mul_f32 v[46:47], v[58:59], v[46:47] op_sel_hi:[0,1]
	ds_read_b128 v[20:23], v73 offset:16640
	v_pk_fma_f32 v[46:47], v[58:59], v[48:49], v[46:47] op_sel:[1,0,0] op_sel_hi:[1,1,1]
	ds_read_b128 v[36:39], v73 offset:16656
	v_pk_fma_f32 v[46:47], v[60:61], v[76:77], v[46:47] op_sel_hi:[0,1,1]
	ds_read_b32 v62, v75 offset:416
	v_pk_fma_f32 v[46:47], v[60:61], v[78:79], v[46:47] op_sel:[1,0,0] op_sel_hi:[1,1,1]
	v_pk_mul_f32 v[68:69], v[68:69], v[44:45] op_sel_hi:[1,0]
	v_pk_mul_f32 v[70:71], v[70:71], v[44:45] op_sel_hi:[1,0]
	v_add_f32_dpp v46, v46, v46 quad_perm:[1,0,3,2] row_mask:0xf bank_mask:0xf bound_ctrl:1
	v_pk_fma_f32 v[68:69], v[58:59], v[50:51], v[68:69]
	v_pk_fma_f32 v[70:71], v[60:61], v[52:53], v[70:71]
	v_add_f32_dpp v46, v46, v46 quad_perm:[2,3,0,1] row_mask:0xf bank_mask:0xf bound_ctrl:1
	ds_read_b128 v[24:27], v74 offset:17152
	ds_read_b128 v[28:31], v74 offset:17408
	v_add_f32_dpp v46, v46, v46 row_half_mirror row_mask:0xf bank_mask:0xf bound_ctrl:1
	ds_read_b128 v[32:35], v74 offset:17664
	ds_write_b32 v72, v47 offset:5120
	v_add_f32_dpp v46, v46, v46 row_mirror row_mask:0xf bank_mask:0xf bound_ctrl:1
	v_pk_fma_f32 v[58:59], v[54:55], v[46:47], v[68:69] op_sel_hi:[1,0,1]
	v_pk_fma_f32 v[60:61], v[56:57], v[46:47], v[70:71] op_sel_hi:[1,0,1]
	s_waitcnt lgkmcnt(8)
; #define LAS __attribute__((address_space(3)))
; #define RW_LDS_WAIT(X) asm volatile("s_waitcnt lgkmcnt(0)" : "+v"(nk##X), "+v"(dd##X), "+v"(bb##X), "+v"(kp##X), "+v"(rr##X), "+v"(vv##X) :: "memory")
; DI void rwkv_scan_phase(int wv, const Params& P, LAS unsigned char* lds) {
;     ...
;                 f32x2 yacc = (f32x2){0.f, 0.f};
;                 unsigned sbt = sba, vbt = vba; LAS float* ybt = yb;
;                 RW_LDS_LOAD(A, 0); RW_LDS_WAIT(A);
; #pragma unroll 1
;                 for (int tt = 0; tt < RW_T; tt += 16) { sbt = sba + (unsigned)tt * 1280u; vbt = vba + (unsigned)tt * 32u; ybt = yb + tt * 128;
;                     RW_LDS_LOAD(B, 1); RW_STEP(A, 0); RW_LDS_WAIT(B);
;                     RW_LDS_LOAD(A, 2); RW_STEP(B, 1); RW_LDS_WAIT(A);
;                     RW_LDS_LOAD(B, 3); RW_STEP(A, 2); RW_LDS_WAIT(B);
;                     RW_LDS_LOAD(A, 4); RW_STEP(B, 3); RW_LDS_WAIT(A);
;                     RW_LDS_LOAD(B, 5); RW_STEP(A, 4); RW_LDS_WAIT(B);
;                     RW_LDS_LOAD(A, 6); RW_STEP(B, 5); RW_LDS_WAIT(A);
;                     RW_LDS_LOAD(B, 7); RW_STEP(A, 6); RW_LDS_WAIT(B);
;                     RW_LDS_LOAD(A, 8); RW_STEP(B, 7); RW_LDS_WAIT(A);
;                     RW_LDS_LOAD(B, 9); RW_STEP(A, 8); RW_LDS_WAIT(B);
;                     RW_LDS_LOAD(A, 10); RW_STEP(B, 9); RW_LDS_WAIT(A);
;                     RW_LDS_LOAD(B, 11); RW_STEP(A, 10); RW_LDS_WAIT(B);
;                     RW_LDS_LOAD(A, 12); RW_STEP(B, 11); RW_LDS_WAIT(A);
;                     RW_LDS_LOAD(B, 13); RW_STEP(A, 12); RW_LDS_WAIT(B);
;                     RW_LDS_LOAD(A, 14); RW_STEP(B, 13); RW_LDS_WAIT(A);
;                     RW_LDS_LOAD(B, 15); RW_STEP(A, 14); RW_LDS_WAIT(B);
;                     RW_LDS_LOAD(A, 16); RW_STEP(B, 15); RW_LDS_WAIT(A);
;                 }
	v_pk_mul_f32 v[0:1], v[58:59], v[0:1] op_sel_hi:[0,1]
	ds_read_b128 v[46:49], v73 offset:17920
	v_pk_fma_f32 v[0:1], v[58:59], v[2:3], v[0:1] op_sel:[1,0,0] op_sel_hi:[1,1,1]
	ds_read_b128 v[76:79], v73 offset:17936
	v_pk_fma_f32 v[0:1], v[60:61], v[16:17], v[0:1] op_sel_hi:[0,1,1]
	ds_read_b32 v44, v75 offset:448
	v_pk_fma_f32 v[0:1], v[60:61], v[18:19], v[0:1] op_sel:[1,0,0] op_sel_hi:[1,1,1]
	v_pk_mul_f32 v[12:13], v[12:13], v[42:43] op_sel_hi:[1,0]
	v_pk_mul_f32 v[14:15], v[14:15], v[42:43] op_sel_hi:[1,0]
	v_add_f32_dpp v0, v0, v0 quad_perm:[1,0,3,2] row_mask:0xf bank_mask:0xf bound_ctrl:1
	v_pk_fma_f32 v[12:13], v[58:59], v[4:5], v[12:13]
	v_pk_fma_f32 v[14:15], v[60:61], v[6:7], v[14:15]
	v_add_f32_dpp v0, v0, v0 quad_perm:[2,3,0,1] row_mask:0xf bank_mask:0xf bound_ctrl:1
	ds_read_b128 v[50:53], v74 offset:18432
	ds_read_b128 v[54:57], v74 offset:18688
	v_add_f32_dpp v0, v0, v0 row_half_mirror row_mask:0xf bank_mask:0xf bound_ctrl:1
	ds_read_b128 v[68:71], v74 offset:18944
	ds_write_b32 v72, v1 offset:5632
	v_add_f32_dpp v0, v0, v0 row_mirror row_mask:0xf bank_mask:0xf bound_ctrl:1
	v_pk_fma_f32 v[58:59], v[8:9], v[0:1], v[12:13] op_sel_hi:[1,0,1]
	v_pk_fma_f32 v[60:61], v[10:11], v[0:1], v[14:15] op_sel_hi:[1,0,1]
	s_waitcnt lgkmcnt(8)
	v_pk_mul_f32 v[20:21], v[58:59], v[20:21] op_sel_hi:[0,1]
	ds_read_b128 v[0:3], v73 offset:19200
	v_pk_fma_f32 v[20:21], v[58:59], v[22:23], v[20:21] op_sel:[1,0,0] op_sel_hi:[1,1,1]
	ds_read_b128 v[16:19], v73 offset:19216
	v_pk_fma_f32 v[20:21], v[60:61], v[36:37], v[20:21] op_sel_hi:[0,1,1]
	ds_read_b32 v42, v75 offset:480
	v_pk_fma_f32 v[20:21], v[60:61], v[38:39], v[20:21] op_sel:[1,0,0] op_sel_hi:[1,1,1]
	v_pk_mul_f32 v[32:33], v[32:33], v[62:63] op_sel_hi:[1,0]
	v_pk_mul_f32 v[34:35], v[34:35], v[62:63] op_sel_hi:[1,0]
	v_add_f32_dpp v20, v20, v20 quad_perm:[1,0,3,2] row_mask:0xf bank_mask:0xf bound_ctrl:1
	v_pk_fma_f32 v[32:33], v[58:59], v[24:25], v[32:33]
	v_pk_fma_f32 v[34:35], v[60:61], v[26:27], v[34:35]
	v_add_f32_dpp v20, v20, v20 quad_perm:[2,3,0,1] row_mask:0xf bank_mask:0xf bound_ctrl:1
	ds_read_b128 v[4:7], v74 offset:19712
	ds_read_b128 v[8:11], v74 offset:19968
	v_add_f32_dpp v20, v20, v20 row_half_mirror row_mask:0xf bank_mask:0xf bound_ctrl:1
	ds_read_b128 v[12:15], v74 offset:20224
	ds_write_b32 v72, v21 offset:6144
	v_add_f32_dpp v20, v20, v20 row_mirror row_mask:0xf bank_mask:0xf bound_ctrl:1
	v_pk_fma_f32 v[58:59], v[28:29], v[20:21], v[32:33] op_sel_hi:[1,0,1]
	v_pk_fma_f32 v[60:61], v[30:31], v[20:21], v[34:35] op_sel_hi:[1,0,1]
	s_waitcnt lgkmcnt(8)
	v_pk_mul_f32 v[46:47], v[58:59], v[46:47] op_sel_hi:[0,1]
	ds_read_b128 v[20:23], v73 offset:20480
	v_pk_fma_f32 v[46:47], v[58:59], v[48:49], v[46:47] op_sel:[1,0,0] op_sel_hi:[1,1,1]
	ds_read_b128 v[36:39], v73 offset:20496
	v_pk_fma_f32 v[46:47], v[60:61], v[76:77], v[46:47] op_sel_hi:[0,1,1]
	ds_read_b32 v62, v75 offset:512
	v_pk_fma_f32 v[46:47], v[60:61], v[78:79], v[46:47] op_sel:[1,0,0] op_sel_hi:[1,1,1]
	v_pk_mul_f32 v[68:69], v[68:69], v[44:45] op_sel_hi:[1,0]
	v_pk_mul_f32 v[70:71], v[70:71], v[44:45] op_sel_hi:[1,0]
	v_add_f32_dpp v46, v46, v46 quad_perm:[1,0,3,2] row_mask:0xf bank_mask:0xf bound_ctrl:1
	v_pk_fma_f32 v[68:69], v[58:59], v[50:51], v[68:69]
	v_pk_fma_f32 v[70:71], v[60:61], v[52:53], v[70:71]
	v_add_f32_dpp v46, v46, v46 quad_perm:[2,3,0,1] row_mask:0xf bank_mask:0xf bound_ctrl:1
	ds_read_b128 v[24:27], v74 offset:20992
	ds_read_b128 v[28:31], v74 offset:21248
	v_add_f32_dpp v46, v46, v46 row_half_mirror row_mask:0xf bank_mask:0xf bound_ctrl:1
	ds_read_b128 v[32:35], v74 offset:21504
	ds_write_b32 v72, v47 offset:6656
	v_add_f32_dpp v46, v46, v46 row_mirror row_mask:0xf bank_mask:0xf bound_ctrl:1
	v_pk_fma_f32 v[58:59], v[54:55], v[46:47], v[68:69] op_sel_hi:[1,0,1]
	v_pk_fma_f32 v[60:61], v[56:57], v[46:47], v[70:71] op_sel_hi:[1,0,1]
	s_waitcnt lgkmcnt(8)
	v_pk_mul_f32 v[0:1], v[58:59], v[0:1] op_sel_hi:[0,1]
	ds_read_b128 v[46:49], v73 offset:21760
	v_pk_fma_f32 v[0:1], v[58:59], v[2:3], v[0:1] op_sel:[1,0,0] op_sel_hi:[1,1,1]
	ds_read_b128 v[76:79], v73 offset:21776
	v_pk_fma_f32 v[0:1], v[60:61], v[16:17], v[0:1] op_sel_hi:[0,1,1]
	ds_read_b32 v44, v75 offset:544
	v_pk_fma_f32 v[0:1], v[60:61], v[18:19], v[0:1] op_sel:[1,0,0] op_sel_hi:[1,1,1]
	v_pk_mul_f32 v[12:13], v[12:13], v[42:43] op_sel_hi:[1,0]
	v_pk_mul_f32 v[14:15], v[14:15], v[42:43] op_sel_hi:[1,0]
	v_add_f32_dpp v0, v0, v0 quad_perm:[1,0,3,2] row_mask:0xf bank_mask:0xf bound_ctrl:1
	v_pk_fma_f32 v[12:13], v[58:59], v[4:5], v[12:13]
	v_pk_fma_f32 v[14:15], v[60:61], v[6:7], v[14:15]
	v_add_f32_dpp v0, v0, v0 quad_perm:[2,3,0,1] row_mask:0xf bank_mask:0xf bound_ctrl:1
	ds_read_b128 v[50:53], v74 offset:22272
	ds_read_b128 v[54:57], v74 offset:22528
	v_add_f32_dpp v0, v0, v0 row_half_mirror row_mask:0xf bank_mask:0xf bound_ctrl:1
	ds_read_b128 v[68:71], v74 offset:22784
	ds_write_b32 v72, v1 offset:7168
	v_add_f32_dpp v0, v0, v0 row_mirror row_mask:0xf bank_mask:0xf bound_ctrl:1
	v_pk_fma_f32 v[58:59], v[8:9], v[0:1], v[12:13] op_sel_hi:[1,0,1]
	v_pk_fma_f32 v[60:61], v[10:11], v[0:1], v[14:15] op_sel_hi:[1,0,1]
	s_waitcnt lgkmcnt(8)
; #define LAS __attribute__((address_space(3)))
; #define RW_LDS_WAIT(X) asm volatile("s_waitcnt lgkmcnt(0)" : "+v"(nk##X), "+v"(dd##X), "+v"(bb##X), "+v"(kp##X), "+v"(rr##X), "+v"(vv##X) :: "memory")
; DI void rwkv_scan_phase(int wv, const Params& P, LAS unsigned char* lds) {
;     ...
;                 f32x2 yacc = (f32x2){0.f, 0.f};
;                 unsigned sbt = sba, vbt = vba; LAS float* ybt = yb;
;                 RW_LDS_LOAD(A, 0); RW_LDS_WAIT(A);
; #pragma unroll 1
;                 for (int tt = 0; tt < RW_T; tt += 16) { sbt = sba + (unsigned)tt * 1280u; vbt = vba + (unsigned)tt * 32u; ybt = yb + tt * 128;
;                     RW_LDS_LOAD(B, 1); RW_STEP(A, 0); RW_LDS_WAIT(B);
;                     RW_LDS_LOAD(A, 2); RW_STEP(B, 1); RW_LDS_WAIT(A);
;                     RW_LDS_LOAD(B, 3); RW_STEP(A, 2); RW_LDS_WAIT(B);
;                     RW_LDS_LOAD(A, 4); RW_STEP(B, 3); RW_LDS_WAIT(A);
;                     RW_LDS_LOAD(B, 5); RW_STEP(A, 4); RW_LDS_WAIT(B);
;                     RW_LDS_LOAD(A, 6); RW_STEP(B, 5); RW_LDS_WAIT(A);
;                     RW_LDS_LOAD(B, 7); RW_STEP(A, 6); RW_LDS_WAIT(B);
;                     RW_LDS_LOAD(A, 8); RW_STEP(B, 7); RW_LDS_WAIT(A);
;                     RW_LDS_LOAD(B, 9); RW_STEP(A, 8); RW_LDS_WAIT(B);
;                     RW_LDS_LOAD(A, 10); RW_STEP(B, 9); RW_LDS_WAIT(A);
;                     RW_LDS_LOAD(B, 11); RW_STEP(A, 10); RW_LDS_WAIT(B);
;                     RW_LDS_LOAD(A, 12); RW_STEP(B, 11); RW_LDS_WAIT(A);
;                     RW_LDS_LOAD(B, 13); RW_STEP(A, 12); RW_LDS_WAIT(B);
;                     RW_LDS_LOAD(A, 14); RW_STEP(B, 13); RW_LDS_WAIT(A);
;                     RW_LDS_LOAD(B, 15); RW_STEP(A, 14); RW_LDS_WAIT(B);
;                     RW_LDS_LOAD(A, 16); RW_STEP(B, 15); RW_LDS_WAIT(A);
;                 }
	v_pk_mul_f32 v[20:21], v[58:59], v[20:21] op_sel_hi:[0,1]
	ds_read_b128 v[0:3], v73 offset:23040
	v_pk_fma_f32 v[20:21], v[58:59], v[22:23], v[20:21] op_sel:[1,0,0] op_sel_hi:[1,1,1]
	ds_read_b128 v[16:19], v73 offset:23056
	v_pk_fma_f32 v[20:21], v[60:61], v[36:37], v[20:21] op_sel_hi:[0,1,1]
	ds_read_b32 v42, v75 offset:576
	v_pk_fma_f32 v[20:21], v[60:61], v[38:39], v[20:21] op_sel:[1,0,0] op_sel_hi:[1,1,1]
	v_pk_mul_f32 v[32:33], v[32:33], v[62:63] op_sel_hi:[1,0]
	v_pk_mul_f32 v[34:35], v[34:35], v[62:63] op_sel_hi:[1,0]
	v_add_f32_dpp v20, v20, v20 quad_perm:[1,0,3,2] row_mask:0xf bank_mask:0xf bound_ctrl:1
	v_pk_fma_f32 v[32:33], v[58:59], v[24:25], v[32:33]
	v_pk_fma_f32 v[34:35], v[60:61], v[26:27], v[34:35]
	v_add_f32_dpp v20, v20, v20 quad_perm:[2,3,0,1] row_mask:0xf bank_mask:0xf bound_ctrl:1
	ds_read_b128 v[4:7], v74 offset:23552
	ds_read_b128 v[8:11], v74 offset:23808
	v_add_f32_dpp v20, v20, v20 row_half_mirror row_mask:0xf bank_mask:0xf bound_ctrl:1
	ds_read_b128 v[12:15], v74 offset:24064
	ds_write_b32 v72, v21 offset:7680
	v_add_f32_dpp v20, v20, v20 row_mirror row_mask:0xf bank_mask:0xf bound_ctrl:1
	v_pk_fma_f32 v[58:59], v[28:29], v[20:21], v[32:33] op_sel_hi:[1,0,1]
	v_pk_fma_f32 v[60:61], v[30:31], v[20:21], v[34:35] op_sel_hi:[1,0,1]
	s_waitcnt lgkmcnt(8)
	v_pk_mul_f32 v[46:47], v[58:59], v[46:47] op_sel_hi:[0,1]
	ds_read_b128 v[20:23], v73 offset:24320
	v_pk_fma_f32 v[46:47], v[58:59], v[48:49], v[46:47] op_sel:[1,0,0] op_sel_hi:[1,1,1]
	ds_read_b128 v[36:39], v73 offset:24336
	v_pk_fma_f32 v[46:47], v[60:61], v[76:77], v[46:47] op_sel_hi:[0,1,1]
	ds_read_b32 v62, v75 offset:608
	v_pk_fma_f32 v[46:47], v[60:61], v[78:79], v[46:47] op_sel:[1,0,0] op_sel_hi:[1,1,1]
	v_pk_mul_f32 v[68:69], v[68:69], v[44:45] op_sel_hi:[1,0]
	v_pk_mul_f32 v[70:71], v[70:71], v[44:45] op_sel_hi:[1,0]
	v_add_f32_dpp v46, v46, v46 quad_perm:[1,0,3,2] row_mask:0xf bank_mask:0xf bound_ctrl:1
	v_pk_fma_f32 v[68:69], v[58:59], v[50:51], v[68:69]
	v_pk_fma_f32 v[70:71], v[60:61], v[52:53], v[70:71]
	v_add_f32_dpp v46, v46, v46 quad_perm:[2,3,0,1] row_mask:0xf bank_mask:0xf bound_ctrl:1
	ds_read_b128 v[24:27], v74 offset:24832
	ds_read_b128 v[28:31], v74 offset:25088
	v_add_f32_dpp v46, v46, v46 row_half_mirror row_mask:0xf bank_mask:0xf bound_ctrl:1
	ds_read_b128 v[32:35], v74 offset:25344
	ds_write_b32 v72, v47 offset:8192
	v_add_f32_dpp v46, v46, v46 row_mirror row_mask:0xf bank_mask:0xf bound_ctrl:1
	v_pk_fma_f32 v[58:59], v[54:55], v[46:47], v[68:69] op_sel_hi:[1,0,1]
	v_pk_fma_f32 v[60:61], v[56:57], v[46:47], v[70:71] op_sel_hi:[1,0,1]
	s_waitcnt lgkmcnt(8)
	v_pk_mul_f32 v[0:1], v[58:59], v[0:1] op_sel_hi:[0,1]
	ds_read_b128 v[46:49], v73 offset:25600
	v_pk_fma_f32 v[0:1], v[58:59], v[2:3], v[0:1] op_sel:[1,0,0] op_sel_hi:[1,1,1]
	ds_read_b128 v[76:79], v73 offset:25616
	v_pk_fma_f32 v[0:1], v[60:61], v[16:17], v[0:1] op_sel_hi:[0,1,1]
	ds_read_b32 v44, v75 offset:640
	v_pk_fma_f32 v[0:1], v[60:61], v[18:19], v[0:1] op_sel:[1,0,0] op_sel_hi:[1,1,1]
	v_pk_mul_f32 v[12:13], v[12:13], v[42:43] op_sel_hi:[1,0]
	v_pk_mul_f32 v[14:15], v[14:15], v[42:43] op_sel_hi:[1,0]
	v_add_f32_dpp v0, v0, v0 quad_perm:[1,0,3,2] row_mask:0xf bank_mask:0xf bound_ctrl:1
	v_pk_fma_f32 v[12:13], v[58:59], v[4:5], v[12:13]
	v_pk_fma_f32 v[14:15], v[60:61], v[6:7], v[14:15]
	v_add_f32_dpp v0, v0, v0 quad_perm:[2,3,0,1] row_mask:0xf bank_mask:0xf bound_ctrl:1
	ds_read_b128 v[50:53], v74 offset:26112
	ds_read_b128 v[54:57], v74 offset:26368
	v_add_f32_dpp v0, v0, v0 row_half_mirror row_mask:0xf bank_mask:0xf bound_ctrl:1
	ds_read_b128 v[68:71], v74 offset:26624
	ds_write_b32 v72, v1 offset:8704
	v_add_f32_dpp v0, v0, v0 row_mirror row_mask:0xf bank_mask:0xf bound_ctrl:1
	v_pk_fma_f32 v[58:59], v[8:9], v[0:1], v[12:13] op_sel_hi:[1,0,1]
	v_pk_fma_f32 v[60:61], v[10:11], v[0:1], v[14:15] op_sel_hi:[1,0,1]
	s_waitcnt lgkmcnt(8)
	v_pk_mul_f32 v[20:21], v[58:59], v[20:21] op_sel_hi:[0,1]
	ds_read_b128 v[0:3], v73 offset:26880
	v_pk_fma_f32 v[20:21], v[58:59], v[22:23], v[20:21] op_sel:[1,0,0] op_sel_hi:[1,1,1]
	ds_read_b128 v[16:19], v73 offset:26896
	v_pk_fma_f32 v[20:21], v[60:61], v[36:37], v[20:21] op_sel_hi:[0,1,1]
	ds_read_b32 v42, v75 offset:672
	v_pk_fma_f32 v[20:21], v[60:61], v[38:39], v[20:21] op_sel:[1,0,0] op_sel_hi:[1,1,1]
	v_pk_mul_f32 v[32:33], v[32:33], v[62:63] op_sel_hi:[1,0]
	v_pk_mul_f32 v[34:35], v[34:35], v[62:63] op_sel_hi:[1,0]
	v_add_f32_dpp v20, v20, v20 quad_perm:[1,0,3,2] row_mask:0xf bank_mask:0xf bound_ctrl:1
	v_pk_fma_f32 v[32:33], v[58:59], v[24:25], v[32:33]
	v_pk_fma_f32 v[34:35], v[60:61], v[26:27], v[34:35]
	v_add_f32_dpp v20, v20, v20 quad_perm:[2,3,0,1] row_mask:0xf bank_mask:0xf bound_ctrl:1
	ds_read_b128 v[4:7], v74 offset:27392
	ds_read_b128 v[8:11], v74 offset:27648
	v_add_f32_dpp v20, v20, v20 row_half_mirror row_mask:0xf bank_mask:0xf bound_ctrl:1
	ds_read_b128 v[12:15], v74 offset:27904
	ds_write_b32 v72, v21 offset:9216
	v_add_f32_dpp v20, v20, v20 row_mirror row_mask:0xf bank_mask:0xf bound_ctrl:1
	v_pk_fma_f32 v[58:59], v[28:29], v[20:21], v[32:33] op_sel_hi:[1,0,1]
	v_pk_fma_f32 v[60:61], v[30:31], v[20:21], v[34:35] op_sel_hi:[1,0,1]
	s_waitcnt lgkmcnt(8)
; #define LAS __attribute__((address_space(3)))
; #define RW_LDS_WAIT(X) asm volatile("s_waitcnt lgkmcnt(0)" : "+v"(nk##X), "+v"(dd##X), "+v"(bb##X), "+v"(kp##X), "+v"(rr##X), "+v"(vv##X) :: "memory")
; DI void rwkv_scan_phase(int wv, const Params& P, LAS unsigned char* lds) {
;     ...
;                 f32x2 yacc = (f32x2){0.f, 0.f};
;                 unsigned sbt = sba, vbt = vba; LAS float* ybt = yb;
;                 RW_LDS_LOAD(A, 0); RW_LDS_WAIT(A);
; #pragma unroll 1
;                 for (int tt = 0; tt < RW_T; tt += 16) { sbt = sba + (unsigned)tt * 1280u; vbt = vba + (unsigned)tt * 32u; ybt = yb + tt * 128;
;                     RW_LDS_LOAD(B, 1); RW_STEP(A, 0); RW_LDS_WAIT(B);
;                     RW_LDS_LOAD(A, 2); RW_STEP(B, 1); RW_LDS_WAIT(A);
;                     RW_LDS_LOAD(B, 3); RW_STEP(A, 2); RW_LDS_WAIT(B);
;                     RW_LDS_LOAD(A, 4); RW_STEP(B, 3); RW_LDS_WAIT(A);
;                     RW_LDS_LOAD(B, 5); RW_STEP(A, 4); RW_LDS_WAIT(B);
;                     RW_LDS_LOAD(A, 6); RW_STEP(B, 5); RW_LDS_WAIT(A);
;                     RW_LDS_LOAD(B, 7); RW_STEP(A, 6); RW_LDS_WAIT(B);
;                     RW_LDS_LOAD(A, 8); RW_STEP(B, 7); RW_LDS_WAIT(A);
;                     RW_LDS_LOAD(B, 9); RW_STEP(A, 8); RW_LDS_WAIT(B);
;                     RW_LDS_LOAD(A, 10); RW_STEP(B, 9); RW_LDS_WAIT(A);
;                     RW_LDS_LOAD(B, 11); RW_STEP(A, 10); RW_LDS_WAIT(B);
;                     RW_LDS_LOAD(A, 12); RW_STEP(B, 11); RW_LDS_WAIT(A);
;                     RW_LDS_LOAD(B, 13); RW_STEP(A, 12); RW_LDS_WAIT(B);
;                     RW_LDS_LOAD(A, 14); RW_STEP(B, 13); RW_LDS_WAIT(A);
;                     RW_LDS_LOAD(B, 15); RW_STEP(A, 14); RW_LDS_WAIT(B);
;                     RW_LDS_LOAD(A, 16); RW_STEP(B, 15); RW_LDS_WAIT(A);
;                 }
	v_pk_mul_f32 v[46:47], v[58:59], v[46:47] op_sel_hi:[0,1]
	ds_read_b128 v[20:23], v73 offset:28160
	v_pk_fma_f32 v[46:47], v[58:59], v[48:49], v[46:47] op_sel:[1,0,0] op_sel_hi:[1,1,1]
	ds_read_b128 v[36:39], v73 offset:28176
	v_pk_fma_f32 v[46:47], v[60:61], v[76:77], v[46:47] op_sel_hi:[0,1,1]
	ds_read_b32 v62, v75 offset:704
	v_pk_fma_f32 v[46:47], v[60:61], v[78:79], v[46:47] op_sel:[1,0,0] op_sel_hi:[1,1,1]
	v_pk_mul_f32 v[68:69], v[68:69], v[44:45] op_sel_hi:[1,0]
	v_pk_mul_f32 v[70:71], v[70:71], v[44:45] op_sel_hi:[1,0]
	v_add_f32_dpp v46, v46, v46 quad_perm:[1,0,3,2] row_mask:0xf bank_mask:0xf bound_ctrl:1
	v_pk_fma_f32 v[68:69], v[58:59], v[50:51], v[68:69]
	v_pk_fma_f32 v[70:71], v[60:61], v[52:53], v[70:71]
	v_add_f32_dpp v46, v46, v46 quad_perm:[2,3,0,1] row_mask:0xf bank_mask:0xf bound_ctrl:1
	ds_read_b128 v[24:27], v74 offset:28672
	ds_read_b128 v[28:31], v74 offset:28928
	v_add_f32_dpp v46, v46, v46 row_half_mirror row_mask:0xf bank_mask:0xf bound_ctrl:1
	ds_read_b128 v[32:35], v74 offset:29184
	ds_write_b32 v72, v47 offset:9728
	v_add_f32_dpp v46, v46, v46 row_mirror row_mask:0xf bank_mask:0xf bound_ctrl:1
	v_pk_fma_f32 v[58:59], v[54:55], v[46:47], v[68:69] op_sel_hi:[1,0,1]
	v_pk_fma_f32 v[60:61], v[56:57], v[46:47], v[70:71] op_sel_hi:[1,0,1]
	s_waitcnt lgkmcnt(8)
	v_pk_mul_f32 v[0:1], v[58:59], v[0:1] op_sel_hi:[0,1]
	ds_read_b128 v[46:49], v73 offset:29440
	v_pk_fma_f32 v[0:1], v[58:59], v[2:3], v[0:1] op_sel:[1,0,0] op_sel_hi:[1,1,1]
	ds_read_b128 v[76:79], v73 offset:29456
	v_pk_fma_f32 v[0:1], v[60:61], v[16:17], v[0:1] op_sel_hi:[0,1,1]
	ds_read_b32 v44, v75 offset:736
	v_pk_fma_f32 v[0:1], v[60:61], v[18:19], v[0:1] op_sel:[1,0,0] op_sel_hi:[1,1,1]
	v_pk_mul_f32 v[12:13], v[12:13], v[42:43] op_sel_hi:[1,0]
	v_pk_mul_f32 v[14:15], v[14:15], v[42:43] op_sel_hi:[1,0]
	v_add_f32_dpp v0, v0, v0 quad_perm:[1,0,3,2] row_mask:0xf bank_mask:0xf bound_ctrl:1
	v_pk_fma_f32 v[12:13], v[58:59], v[4:5], v[12:13]
	v_pk_fma_f32 v[14:15], v[60:61], v[6:7], v[14:15]
	v_add_f32_dpp v0, v0, v0 quad_perm:[2,3,0,1] row_mask:0xf bank_mask:0xf bound_ctrl:1
	ds_read_b128 v[50:53], v74 offset:29952
	ds_read_b128 v[54:57], v74 offset:30208
	v_add_f32_dpp v0, v0, v0 row_half_mirror row_mask:0xf bank_mask:0xf bound_ctrl:1
	ds_read_b128 v[68:71], v74 offset:30464
	ds_write_b32 v72, v1 offset:10240
	v_add_f32_dpp v0, v0, v0 row_mirror row_mask:0xf bank_mask:0xf bound_ctrl:1
	v_pk_fma_f32 v[58:59], v[8:9], v[0:1], v[12:13] op_sel_hi:[1,0,1]
	v_pk_fma_f32 v[60:61], v[10:11], v[0:1], v[14:15] op_sel_hi:[1,0,1]
	s_waitcnt lgkmcnt(8)
	v_pk_mul_f32 v[20:21], v[58:59], v[20:21] op_sel_hi:[0,1]
	ds_read_b128 v[0:3], v73 offset:30720
	v_pk_fma_f32 v[20:21], v[58:59], v[22:23], v[20:21] op_sel:[1,0,0] op_sel_hi:[1,1,1]
	ds_read_b128 v[16:19], v73 offset:30736
	v_pk_fma_f32 v[20:21], v[60:61], v[36:37], v[20:21] op_sel_hi:[0,1,1]
	ds_read_b32 v42, v75 offset:768
	v_pk_fma_f32 v[20:21], v[60:61], v[38:39], v[20:21] op_sel:[1,0,0] op_sel_hi:[1,1,1]
	v_pk_mul_f32 v[32:33], v[32:33], v[62:63] op_sel_hi:[1,0]
	v_pk_mul_f32 v[34:35], v[34:35], v[62:63] op_sel_hi:[1,0]
	v_add_f32_dpp v20, v20, v20 quad_perm:[1,0,3,2] row_mask:0xf bank_mask:0xf bound_ctrl:1
	v_pk_fma_f32 v[32:33], v[58:59], v[24:25], v[32:33]
	v_pk_fma_f32 v[34:35], v[60:61], v[26:27], v[34:35]
	v_add_f32_dpp v20, v20, v20 quad_perm:[2,3,0,1] row_mask:0xf bank_mask:0xf bound_ctrl:1
	ds_read_b128 v[4:7], v74 offset:31232
	ds_read_b128 v[8:11], v74 offset:31488
	v_add_f32_dpp v20, v20, v20 row_half_mirror row_mask:0xf bank_mask:0xf bound_ctrl:1
	ds_read_b128 v[12:15], v74 offset:31744
	ds_write_b32 v72, v21 offset:10752
	v_add_f32_dpp v20, v20, v20 row_mirror row_mask:0xf bank_mask:0xf bound_ctrl:1
	v_pk_fma_f32 v[58:59], v[28:29], v[20:21], v[32:33] op_sel_hi:[1,0,1]
	v_pk_fma_f32 v[60:61], v[30:31], v[20:21], v[34:35] op_sel_hi:[1,0,1]
	s_waitcnt lgkmcnt(8)
	v_pk_mul_f32 v[46:47], v[58:59], v[46:47] op_sel_hi:[0,1]
	ds_read_b128 v[20:23], v73 offset:32000
	v_pk_fma_f32 v[46:47], v[58:59], v[48:49], v[46:47] op_sel:[1,0,0] op_sel_hi:[1,1,1]
	ds_read_b128 v[36:39], v73 offset:32016
	v_pk_fma_f32 v[46:47], v[60:61], v[76:77], v[46:47] op_sel_hi:[0,1,1]
	ds_read_b32 v62, v75 offset:800
	v_pk_fma_f32 v[46:47], v[60:61], v[78:79], v[46:47] op_sel:[1,0,0] op_sel_hi:[1,1,1]
	v_pk_mul_f32 v[68:69], v[68:69], v[44:45] op_sel_hi:[1,0]
	v_pk_mul_f32 v[70:71], v[70:71], v[44:45] op_sel_hi:[1,0]
	v_add_f32_dpp v46, v46, v46 quad_perm:[1,0,3,2] row_mask:0xf bank_mask:0xf bound_ctrl:1
	v_pk_fma_f32 v[68:69], v[58:59], v[50:51], v[68:69]
	v_pk_fma_f32 v[70:71], v[60:61], v[52:53], v[70:71]
	v_add_f32_dpp v46, v46, v46 quad_perm:[2,3,0,1] row_mask:0xf bank_mask:0xf bound_ctrl:1
	ds_read_b128 v[24:27], v74 offset:32512
	ds_read_b128 v[28:31], v74 offset:32768
	v_add_f32_dpp v46, v46, v46 row_half_mirror row_mask:0xf bank_mask:0xf bound_ctrl:1
	ds_read_b128 v[32:35], v74 offset:33024
	ds_write_b32 v72, v47 offset:11264
	v_add_f32_dpp v46, v46, v46 row_mirror row_mask:0xf bank_mask:0xf bound_ctrl:1
	v_pk_fma_f32 v[58:59], v[54:55], v[46:47], v[68:69] op_sel_hi:[1,0,1]
	v_pk_fma_f32 v[60:61], v[56:57], v[46:47], v[70:71] op_sel_hi:[1,0,1]
	s_waitcnt lgkmcnt(8)
; #define LAS __attribute__((address_space(3)))
; #define RW_LDS_WAIT(X) asm volatile("s_waitcnt lgkmcnt(0)" : "+v"(nk##X), "+v"(dd##X), "+v"(bb##X), "+v"(kp##X), "+v"(rr##X), "+v"(vv##X) :: "memory")
; DI void rwkv_scan_phase(int wv, const Params& P, LAS unsigned char* lds) {
;     ...
;                 f32x2 yacc = (f32x2){0.f, 0.f};
;                 unsigned sbt = sba, vbt = vba; LAS float* ybt = yb;
;                 RW_LDS_LOAD(A, 0); RW_LDS_WAIT(A);
; #pragma unroll 1
;                 for (int tt = 0; tt < RW_T; tt += 16) { sbt = sba + (unsigned)tt * 1280u; vbt = vba + (unsigned)tt * 32u; ybt = yb + tt * 128;
;                     RW_LDS_LOAD(B, 1); RW_STEP(A, 0); RW_LDS_WAIT(B);
;                     RW_LDS_LOAD(A, 2); RW_STEP(B, 1); RW_LDS_WAIT(A);
;                     RW_LDS_LOAD(B, 3); RW_STEP(A, 2); RW_LDS_WAIT(B);
;                     RW_LDS_LOAD(A, 4); RW_STEP(B, 3); RW_LDS_WAIT(A);
;                     RW_LDS_LOAD(B, 5); RW_STEP(A, 4); RW_LDS_WAIT(B);
;                     RW_LDS_LOAD(A, 6); RW_STEP(B, 5); RW_LDS_WAIT(A);
;                     RW_LDS_LOAD(B, 7); RW_STEP(A, 6); RW_LDS_WAIT(B);
;                     RW_LDS_LOAD(A, 8); RW_STEP(B, 7); RW_LDS_WAIT(A);
;                     RW_LDS_LOAD(B, 9); RW_STEP(A, 8); RW_LDS_WAIT(B);
;                     RW_LDS_LOAD(A, 10); RW_STEP(B, 9); RW_LDS_WAIT(A);
;                     RW_LDS_LOAD(B, 11); RW_STEP(A, 10); RW_LDS_WAIT(B);
;                     RW_LDS_LOAD(A, 12); RW_STEP(B, 11); RW_LDS_WAIT(A);
;                     RW_LDS_LOAD(B, 13); RW_STEP(A, 12); RW_LDS_WAIT(B);
;                     RW_LDS_LOAD(A, 14); RW_STEP(B, 13); RW_LDS_WAIT(A);
;                     RW_LDS_LOAD(B, 15); RW_STEP(A, 14); RW_LDS_WAIT(B);
;                     RW_LDS_LOAD(A, 16); RW_STEP(B, 15); RW_LDS_WAIT(A);
;                 }
	v_pk_mul_f32 v[0:1], v[58:59], v[0:1] op_sel_hi:[0,1]
	ds_read_b128 v[46:49], v73 offset:33280
	v_pk_fma_f32 v[0:1], v[58:59], v[2:3], v[0:1] op_sel:[1,0,0] op_sel_hi:[1,1,1]
	ds_read_b128 v[76:79], v73 offset:33296
	v_pk_fma_f32 v[0:1], v[60:61], v[16:17], v[0:1] op_sel_hi:[0,1,1]
	ds_read_b32 v44, v75 offset:832
	v_pk_fma_f32 v[0:1], v[60:61], v[18:19], v[0:1] op_sel:[1,0,0] op_sel_hi:[1,1,1]
	v_pk_mul_f32 v[12:13], v[12:13], v[42:43] op_sel_hi:[1,0]
	v_pk_mul_f32 v[14:15], v[14:15], v[42:43] op_sel_hi:[1,0]
	v_add_f32_dpp v0, v0, v0 quad_perm:[1,0,3,2] row_mask:0xf bank_mask:0xf bound_ctrl:1
	v_pk_fma_f32 v[12:13], v[58:59], v[4:5], v[12:13]
	v_pk_fma_f32 v[14:15], v[60:61], v[6:7], v[14:15]
	v_add_f32_dpp v0, v0, v0 quad_perm:[2,3,0,1] row_mask:0xf bank_mask:0xf bound_ctrl:1
	ds_read_b128 v[50:53], v74 offset:33792
	ds_read_b128 v[54:57], v74 offset:34048
	v_add_f32_dpp v0, v0, v0 row_half_mirror row_mask:0xf bank_mask:0xf bound_ctrl:1
	ds_read_b128 v[68:71], v74 offset:34304
	ds_write_b32 v72, v1 offset:11776
	v_add_f32_dpp v0, v0, v0 row_mirror row_mask:0xf bank_mask:0xf bound_ctrl:1
	v_pk_fma_f32 v[58:59], v[8:9], v[0:1], v[12:13] op_sel_hi:[1,0,1]
	v_pk_fma_f32 v[60:61], v[10:11], v[0:1], v[14:15] op_sel_hi:[1,0,1]
	s_waitcnt lgkmcnt(8)
	v_pk_mul_f32 v[20:21], v[58:59], v[20:21] op_sel_hi:[0,1]
	ds_read_b128 v[0:3], v73 offset:34560
	v_pk_fma_f32 v[20:21], v[58:59], v[22:23], v[20:21] op_sel:[1,0,0] op_sel_hi:[1,1,1]
	ds_read_b128 v[16:19], v73 offset:34576
	v_pk_fma_f32 v[20:21], v[60:61], v[36:37], v[20:21] op_sel_hi:[0,1,1]
	ds_read_b32 v42, v75 offset:864
	v_pk_fma_f32 v[20:21], v[60:61], v[38:39], v[20:21] op_sel:[1,0,0] op_sel_hi:[1,1,1]
	v_pk_mul_f32 v[32:33], v[32:33], v[62:63] op_sel_hi:[1,0]
	v_pk_mul_f32 v[34:35], v[34:35], v[62:63] op_sel_hi:[1,0]
	v_add_f32_dpp v20, v20, v20 quad_perm:[1,0,3,2] row_mask:0xf bank_mask:0xf bound_ctrl:1
	v_pk_fma_f32 v[32:33], v[58:59], v[24:25], v[32:33]
	v_pk_fma_f32 v[34:35], v[60:61], v[26:27], v[34:35]
	v_add_f32_dpp v20, v20, v20 quad_perm:[2,3,0,1] row_mask:0xf bank_mask:0xf bound_ctrl:1
	ds_read_b128 v[4:7], v74 offset:35072
	ds_read_b128 v[8:11], v74 offset:35328
	v_add_f32_dpp v20, v20, v20 row_half_mirror row_mask:0xf bank_mask:0xf bound_ctrl:1
	ds_read_b128 v[12:15], v74 offset:35584
	ds_write_b32 v72, v21 offset:12288
	v_add_f32_dpp v20, v20, v20 row_mirror row_mask:0xf bank_mask:0xf bound_ctrl:1
	v_pk_fma_f32 v[58:59], v[28:29], v[20:21], v[32:33] op_sel_hi:[1,0,1]
	v_pk_fma_f32 v[60:61], v[30:31], v[20:21], v[34:35] op_sel_hi:[1,0,1]
	s_waitcnt lgkmcnt(8)
	v_pk_mul_f32 v[46:47], v[58:59], v[46:47] op_sel_hi:[0,1]
	ds_read_b128 v[20:23], v73 offset:35840
	v_pk_fma_f32 v[46:47], v[58:59], v[48:49], v[46:47] op_sel:[1,0,0] op_sel_hi:[1,1,1]
	ds_read_b128 v[36:39], v73 offset:35856
	v_pk_fma_f32 v[46:47], v[60:61], v[76:77], v[46:47] op_sel_hi:[0,1,1]
	ds_read_b32 v62, v75 offset:896
	v_pk_fma_f32 v[46:47], v[60:61], v[78:79], v[46:47] op_sel:[1,0,0] op_sel_hi:[1,1,1]
	v_pk_mul_f32 v[68:69], v[68:69], v[44:45] op_sel_hi:[1,0]
	v_pk_mul_f32 v[70:71], v[70:71], v[44:45] op_sel_hi:[1,0]
	v_add_f32_dpp v46, v46, v46 quad_perm:[1,0,3,2] row_mask:0xf bank_mask:0xf bound_ctrl:1
	v_pk_fma_f32 v[68:69], v[58:59], v[50:51], v[68:69]
	v_pk_fma_f32 v[70:71], v[60:61], v[52:53], v[70:71]
	v_add_f32_dpp v46, v46, v46 quad_perm:[2,3,0,1] row_mask:0xf bank_mask:0xf bound_ctrl:1
	ds_read_b128 v[24:27], v74 offset:36352
	ds_read_b128 v[28:31], v74 offset:36608
	v_add_f32_dpp v46, v46, v46 row_half_mirror row_mask:0xf bank_mask:0xf bound_ctrl:1
	ds_read_b128 v[32:35], v74 offset:36864
	ds_write_b32 v72, v47 offset:12800
	v_add_f32_dpp v46, v46, v46 row_mirror row_mask:0xf bank_mask:0xf bound_ctrl:1
	v_pk_fma_f32 v[58:59], v[54:55], v[46:47], v[68:69] op_sel_hi:[1,0,1]
	v_pk_fma_f32 v[60:61], v[56:57], v[46:47], v[70:71] op_sel_hi:[1,0,1]
	s_waitcnt lgkmcnt(8)
	v_pk_mul_f32 v[0:1], v[58:59], v[0:1] op_sel_hi:[0,1]
	ds_read_b128 v[46:49], v73 offset:37120
	v_pk_fma_f32 v[0:1], v[58:59], v[2:3], v[0:1] op_sel:[1,0,0] op_sel_hi:[1,1,1]
	ds_read_b128 v[76:79], v73 offset:37136
	v_pk_fma_f32 v[0:1], v[60:61], v[16:17], v[0:1] op_sel_hi:[0,1,1]
	ds_read_b32 v44, v75 offset:928
	v_pk_fma_f32 v[0:1], v[60:61], v[18:19], v[0:1] op_sel:[1,0,0] op_sel_hi:[1,1,1]
	v_pk_mul_f32 v[12:13], v[12:13], v[42:43] op_sel_hi:[1,0]
	v_pk_mul_f32 v[14:15], v[14:15], v[42:43] op_sel_hi:[1,0]
	v_add_f32_dpp v0, v0, v0 quad_perm:[1,0,3,2] row_mask:0xf bank_mask:0xf bound_ctrl:1
	v_pk_fma_f32 v[12:13], v[58:59], v[4:5], v[12:13]
	v_pk_fma_f32 v[14:15], v[60:61], v[6:7], v[14:15]
	v_add_f32_dpp v0, v0, v0 quad_perm:[2,3,0,1] row_mask:0xf bank_mask:0xf bound_ctrl:1
	ds_read_b128 v[50:53], v74 offset:37632
	ds_read_b128 v[54:57], v74 offset:37888
	v_add_f32_dpp v0, v0, v0 row_half_mirror row_mask:0xf bank_mask:0xf bound_ctrl:1
	ds_read_b128 v[68:71], v74 offset:38144
	ds_write_b32 v72, v1 offset:13312
	v_add_f32_dpp v0, v0, v0 row_mirror row_mask:0xf bank_mask:0xf bound_ctrl:1
	v_pk_fma_f32 v[58:59], v[8:9], v[0:1], v[12:13] op_sel_hi:[1,0,1]
	v_pk_fma_f32 v[60:61], v[10:11], v[0:1], v[14:15] op_sel_hi:[1,0,1]
	s_waitcnt lgkmcnt(8)
; #define RW_LDS_WAIT(X) asm volatile("s_waitcnt lgkmcnt(0)" : "+v"(nk##X), "+v"(dd##X), "+v"(bb##X), "+v"(kp##X), "+v"(rr##X), "+v"(vv##X) :: "memory")
; DI void rwkv_scan_phase(int wv, const Params& P, LAS unsigned char* lds) {
;     ...
;                 for (int tt = 0; tt < RW_T; tt += 16) { sbt = sba + (unsigned)tt * 1280u; vbt = vba + (unsigned)tt * 32u; ybt = yb + tt * 128;
;                     RW_LDS_LOAD(B, 1); RW_STEP(A, 0); RW_LDS_WAIT(B);
;                     RW_LDS_LOAD(A, 2); RW_STEP(B, 1); RW_LDS_WAIT(A);
;                     RW_LDS_LOAD(B, 3); RW_STEP(A, 2); RW_LDS_WAIT(B);
;                     RW_LDS_LOAD(A, 4); RW_STEP(B, 3); RW_LDS_WAIT(A);
;                     RW_LDS_LOAD(B, 5); RW_STEP(A, 4); RW_LDS_WAIT(B);
;                     RW_LDS_LOAD(A, 6); RW_STEP(B, 5); RW_LDS_WAIT(A);
;                     RW_LDS_LOAD(B, 7); RW_STEP(A, 6); RW_LDS_WAIT(B);
;                     RW_LDS_LOAD(A, 8); RW_STEP(B, 7); RW_LDS_WAIT(A);
;                     RW_LDS_LOAD(B, 9); RW_STEP(A, 8); RW_LDS_WAIT(B);
;                     RW_LDS_LOAD(A, 10); RW_STEP(B, 9); RW_LDS_WAIT(A);
;                     RW_LDS_LOAD(B, 11); RW_STEP(A, 10); RW_LDS_WAIT(B);
;                     RW_LDS_LOAD(A, 12); RW_STEP(B, 11); RW_LDS_WAIT(A);
;                     RW_LDS_LOAD(B, 13); RW_STEP(A, 12); RW_LDS_WAIT(B);
;                     RW_LDS_LOAD(A, 14); RW_STEP(B, 13); RW_LDS_WAIT(A);
;                     RW_LDS_LOAD(B, 15); RW_STEP(A, 14); RW_LDS_WAIT(B);
;                     RW_LDS_LOAD(A, 16); RW_STEP(B, 15); RW_LDS_WAIT(A);
;                 }
;                 yb[(RW_T - 1) * 128] = yacc[0] + yacc[1];
;     ...
;                 __syncthreads();
	v_pk_mul_f32 v[20:21], v[58:59], v[20:21] op_sel_hi:[0,1]
	ds_read_b128 v[0:3], v73 offset:38400
	v_pk_fma_f32 v[20:21], v[58:59], v[22:23], v[20:21] op_sel:[1,0,0] op_sel_hi:[1,1,1]
	ds_read_b128 v[16:19], v73 offset:38416
	v_pk_fma_f32 v[20:21], v[60:61], v[36:37], v[20:21] op_sel_hi:[0,1,1]
	ds_read_b32 v42, v75 offset:960
	v_pk_fma_f32 v[20:21], v[60:61], v[38:39], v[20:21] op_sel:[1,0,0] op_sel_hi:[1,1,1]
	v_pk_mul_f32 v[32:33], v[32:33], v[62:63] op_sel_hi:[1,0]
	v_pk_mul_f32 v[34:35], v[34:35], v[62:63] op_sel_hi:[1,0]
	v_add_f32_dpp v20, v20, v20 quad_perm:[1,0,3,2] row_mask:0xf bank_mask:0xf bound_ctrl:1
	v_pk_fma_f32 v[32:33], v[58:59], v[24:25], v[32:33]
	v_pk_fma_f32 v[34:35], v[60:61], v[26:27], v[34:35]
	v_add_f32_dpp v20, v20, v20 quad_perm:[2,3,0,1] row_mask:0xf bank_mask:0xf bound_ctrl:1
	ds_read_b128 v[4:7], v74 offset:38912
	ds_read_b128 v[8:11], v74 offset:39168
	v_add_f32_dpp v20, v20, v20 row_half_mirror row_mask:0xf bank_mask:0xf bound_ctrl:1
	ds_read_b128 v[12:15], v74 offset:39424
	ds_write_b32 v72, v21 offset:13824
	v_add_f32_dpp v20, v20, v20 row_mirror row_mask:0xf bank_mask:0xf bound_ctrl:1
	v_pk_fma_f32 v[58:59], v[28:29], v[20:21], v[32:33] op_sel_hi:[1,0,1]
	v_pk_fma_f32 v[60:61], v[30:31], v[20:21], v[34:35] op_sel_hi:[1,0,1]
	s_waitcnt lgkmcnt(8)
	v_pk_mul_f32 v[46:47], v[58:59], v[46:47] op_sel_hi:[0,1]
	ds_read_b128 v[20:23], v73 offset:39680
	v_pk_fma_f32 v[46:47], v[58:59], v[48:49], v[46:47] op_sel:[1,0,0] op_sel_hi:[1,1,1]
	ds_read_b128 v[36:39], v73 offset:39696
	v_pk_fma_f32 v[46:47], v[60:61], v[76:77], v[46:47] op_sel_hi:[0,1,1]
	ds_read_b32 v62, v75 offset:992
	v_pk_fma_f32 v[46:47], v[60:61], v[78:79], v[46:47] op_sel:[1,0,0] op_sel_hi:[1,1,1]
	v_pk_mul_f32 v[68:69], v[68:69], v[44:45] op_sel_hi:[1,0]
	v_pk_mul_f32 v[70:71], v[70:71], v[44:45] op_sel_hi:[1,0]
	v_add_f32_dpp v46, v46, v46 quad_perm:[1,0,3,2] row_mask:0xf bank_mask:0xf bound_ctrl:1
	v_pk_fma_f32 v[68:69], v[58:59], v[50:51], v[68:69]
	v_pk_fma_f32 v[70:71], v[60:61], v[52:53], v[70:71]
	v_add_f32_dpp v46, v46, v46 quad_perm:[2,3,0,1] row_mask:0xf bank_mask:0xf bound_ctrl:1
	ds_read_b128 v[24:27], v74 offset:40192
	ds_read_b128 v[28:31], v74 offset:40448
	v_add_f32_dpp v46, v46, v46 row_half_mirror row_mask:0xf bank_mask:0xf bound_ctrl:1
	ds_read_b128 v[32:35], v74 offset:40704
	ds_write_b32 v72, v47 offset:14336
	v_add_f32_dpp v46, v46, v46 row_mirror row_mask:0xf bank_mask:0xf bound_ctrl:1
	v_pk_fma_f32 v[58:59], v[54:55], v[46:47], v[68:69] op_sel_hi:[1,0,1]
	v_pk_fma_f32 v[60:61], v[56:57], v[46:47], v[70:71] op_sel_hi:[1,0,1]
	s_waitcnt lgkmcnt(8)
	v_pk_mul_f32 v[0:1], v[58:59], v[0:1] op_sel_hi:[0,1]
	v_pk_mul_f32 v[12:13], v[12:13], v[42:43] op_sel_hi:[1,0]
	v_pk_fma_f32 v[0:1], v[58:59], v[2:3], v[0:1] op_sel:[1,0,0] op_sel_hi:[1,1,1]
	v_pk_mul_f32 v[14:15], v[14:15], v[42:43] op_sel_hi:[1,0]
	v_pk_fma_f32 v[0:1], v[60:61], v[16:17], v[0:1] op_sel_hi:[0,1,1]
	v_pk_fma_f32 v[12:13], v[58:59], v[4:5], v[12:13]
	v_pk_fma_f32 v[0:1], v[60:61], v[18:19], v[0:1] op_sel:[1,0,0] op_sel_hi:[1,1,1]
	v_pk_fma_f32 v[14:15], v[60:61], v[6:7], v[14:15]
	ds_write_b32 v72, v1 offset:14848
	v_add_f32_dpp v0, v0, v0 quad_perm:[1,0,3,2] row_mask:0xf bank_mask:0xf bound_ctrl:1
	ds_read_b128 v[46:49], v40
	s_nop 0
	v_add_f32_dpp v0, v0, v0 quad_perm:[2,3,0,1] row_mask:0xf bank_mask:0xf bound_ctrl:1
	s_nop 0
	s_nop 0
	v_add_f32_dpp v0, v0, v0 row_half_mirror row_mask:0xf bank_mask:0xf bound_ctrl:1
	s_nop 0
	s_nop 0
	v_add_f32_dpp v0, v0, v0 row_mirror row_mask:0xf bank_mask:0xf bound_ctrl:1
	v_pk_fma_f32 v[58:59], v[8:9], v[0:1], v[12:13] op_sel_hi:[1,0,1]
	v_pk_fma_f32 v[60:61], v[10:11], v[0:1], v[14:15] op_sel_hi:[1,0,1]
	s_waitcnt lgkmcnt(3)
	v_pk_mul_f32 v[20:21], v[58:59], v[20:21] op_sel_hi:[0,1]
	v_pk_mul_f32 v[32:33], v[32:33], v[62:63] op_sel_hi:[1,0]
	v_pk_fma_f32 v[20:21], v[58:59], v[22:23], v[20:21] op_sel:[1,0,0] op_sel_hi:[1,1,1]
	v_pk_mul_f32 v[34:35], v[34:35], v[62:63] op_sel_hi:[1,0]
	v_pk_fma_f32 v[20:21], v[60:61], v[36:37], v[20:21] op_sel_hi:[0,1,1]
	v_pk_fma_f32 v[32:33], v[58:59], v[24:25], v[32:33]
	v_pk_fma_f32 v[20:21], v[60:61], v[38:39], v[20:21] op_sel:[1,0,0] op_sel_hi:[1,1,1]
	v_pk_fma_f32 v[34:35], v[60:61], v[26:27], v[34:35]
	ds_write_b32 v72, v21 offset:15360
	v_add_f32_dpp v20, v20, v20 quad_perm:[1,0,3,2] row_mask:0xf bank_mask:0xf bound_ctrl:1
	s_nop 0
	s_nop 0
	v_add_f32_dpp v20, v20, v20 quad_perm:[2,3,0,1] row_mask:0xf bank_mask:0xf bound_ctrl:1
	s_nop 0
	s_nop 0
	v_add_f32_dpp v20, v20, v20 row_half_mirror row_mask:0xf bank_mask:0xf bound_ctrl:1
	s_nop 0
	s_nop 0
	v_add_f32_dpp v20, v20, v20 row_mirror row_mask:0xf bank_mask:0xf bound_ctrl:1
	v_pk_fma_f32 v[58:59], v[28:29], v[20:21], v[32:33] op_sel_hi:[1,0,1]
	v_pk_fma_f32 v[60:61], v[30:31], v[20:21], v[34:35] op_sel_hi:[1,0,1]
	s_waitcnt lgkmcnt(1)
	v_pk_mul_f32 v[64:65], v[46:47], v[58:59]
	s_add_i32 s47, s47, 1
	v_pk_fma_f32 v[64:65], v[48:49], v[60:61], v[64:65]
	s_cmpk_eq_i32 s47, 0x100
	v_add_f32_e32 v64, v64, v65
	ds_write_b32 v72, v64 offset:15872
	s_waitcnt lgkmcnt(0)
	s_barrier
	s_cbranch_scc0 .Lscan_chunk

; DI void rwkv_scan_phase(int wv, const Params& P, LAS unsigned char* lds) {
;     ...
;         if (wave >= 2) {
;             const int ch = h * 64 + lane;
;             const float kkw = P.in[35][ch], kaw = P.in[36][ch], rkw = P.in[37][ch];
;             const int hf = lane >> 5, c2 = lane & 31, chp = h * 64 + 2 * c2;
;             const f32x2 kkw2 = *(const f32x2*)(P.in[35] + chp), kaw2 = *(const f32x2*)(P.in[36] + chp), rkw2 = *(const f32x2*)(P.in[37] + chp);
;             unsigned gk[3], ga[3], gr[3], gl[3]; float gv[3];
;     ...
;             RW_LOADG(0)
.LBB0_3185:
	s_andn2_saveexec_b64 s[40:41], s[20:21]
	s_cbranch_execz .LBB0_3174
	v_readfirstlane_b32 s55, v41
	s_mov_b32 s68, s55
	s_and_b32 s66, s55, 2
	s_cmp_lg_u32 s66, 0
	s_cbranch_scc1 .Lprod_idle
	s_lshr_b32 s66, s55, 1
	s_and_b32 s55, s55, 1
	s_or_b32 s55, s55, s66
	s_and_b32 s67, s46, 7
	s_bfe_u32 s59, s46, 0x40003
	s_lshr_b32 s60, s46, 7
	s_lshl_b32 s60, s60, 13
	s_lshl_b32 s66, s55, 3
	s_add_i32 s60, s60, s66
	v_mbcnt_lo_u32_b32 v0, -1, 0
	v_mbcnt_hi_u32_b32 v0, -1, v0
	v_and_b32_e32 v1, 31, v0
	v_lshrrev_b32_e32 v31, 5, v0
	s_lshl_b32 s61, s59, 6
	v_lshl_add_u32 v32, v1, 1, s61
	v_lshlrev_b32_e32 v33, 2, v32
	global_load_dwordx2 v[4:5], v33, s[24:25]
	global_load_dwordx2 v[6:7], v33, s[26:27]
	global_load_dwordx2 v[8:9], v33, s[38:39]
	v_add_u32_e32 v34, s60, v31
	v_lshlrev_b32_e32 v35, 11, v34
	v_lshl_add_u32 v12, v32, 1, v35
	v_add_u32_e32 v13, 0x1000, v12
	v_add_u32_e32 v14, 0x2000, v12
	v_add_u32_e32 v15, 0x3000, v12
	v_and_b32_e32 v36, 7, v0
	s_lshl_b32 s66, s67, 3
	s_add_i32 s66, s66, s61
	v_add_u32_e32 v37, s66, v36
	v_lshl_add_u32 v16, v37, 1, v35
	v_add_u32_e32 v17, 0x1000, v16
	v_add_u32_e32 v18, 0x2000, v16
	v_add_u32_e32 v19, 0x3000, v16
	s_lshl_b32 s66, s55, 3
	v_add_u32_e32 v37, s66, v31
	v_mul_u32_u24_e32 v2, 0x500, v37
	v_lshl_add_u32 v2, v1, 3, v2
	v_lshlrev_b32_e32 v3, 5, v37
	v_lshl_add_u32 v3, v1, 2, v3
	v_add_u32_e32 v3, 0x14000, v3
	s_lshl_b32 s66, s59, 2
	v_lshl_add_u32 v10, v34, 6, s66
	v_lshrrev_b32_e32 v37, 3, v0
	s_lshl_b32 s66, s55, 3
	v_add_u32_e32 v37, s66, v37
	v_lshlrev_b32_e32 v11, 9, v37
	v_lshl_add_u32 v11, v36, 6, v11
	v_add_u32_e32 v11, 0x14800, v11
	s_lshr_b32 s66, s46, 7
	s_lshl_b32 s66, s66, 13
	v_add_u32_e32 v37, s66, v37
	v_lshlrev_b32_e32 v37, 11, v37
	s_lshl_b32 s66, s67, 3
	s_add_i32 s66, s66, s61
	v_add_u32_e32 v38, s66, v36
	v_lshl_add_u32 v20, v38, 1, v37
	v_or_b32_e32 v38, s67, v1
	v_cmp_eq_u32_e64 s[42:43], 0, v38
	s_mov_b32 s57, -1
	s_mov_b32 s67, 0
	s_add_u32 s60, s28, s67
	s_addc_u32 s61, s29, 0
	global_load_dword v44, v12, s[60:61]
	global_load_dword v49, v13, s[60:61]
	global_load_dword v54, v14, s[60:61]
	global_load_dword v59, v15, s[60:61]
	s_add_u32 s60, s34, s67
	s_addc_u32 s61, s35, 0
	global_load_dword v45, v12, s[60:61]
	global_load_dword v50, v13, s[60:61]
	global_load_dword v55, v14, s[60:61]
	global_load_dword v60, v15, s[60:61]
	s_add_u32 s60, s22, s67
	s_addc_u32 s61, s23, 0
	global_load_dword v46, v12, s[60:61]
	global_load_dword v51, v13, s[60:61]
	global_load_dword v56, v14, s[60:61]
	global_load_dword v61, v15, s[60:61]
	s_add_u32 s60, s36, s67
	s_addc_u32 s61, s37, 0
	global_load_dword v47, v12, s[60:61]
	global_load_dword v52, v13, s[60:61]
	global_load_dword v57, v14, s[60:61]
	global_load_dword v62, v15, s[60:61]
	s_add_u32 s60, s30, s67
	s_addc_u32 s61, s31, 0
	global_load_ushort v48, v16, s[60:61]
	global_load_ushort v53, v17, s[60:61]
	global_load_ushort v58, v18, s[60:61]
	global_load_ushort v63, v19, s[60:61]
	s_add_u32 s60, s22, s67
	s_addc_u32 s61, s23, 0
	s_sub_u32 s60, s60, 0x800
	s_subb_u32 s61, s61, 0
	global_load_dword v0, v12, s[60:61]
	global_load_dword v40, v13, s[60:61]
	global_load_dword v43, v14, s[60:61]
	global_load_dword v41, v15, s[60:61]

; #define LAS __attribute__((address_space(3)))
; DI float bflo(unsigned u) { return __uint_as_float(u << 16); }
; DI float bfhi(unsigned u) { return __uint_as_float(u & 0xffff0000u); }
; template <int CTRL> DI float dpp_f(float v) { return __builtin_bit_cast(float, __builtin_amdgcn_update_dpp(0, __builtin_bit_cast(int, v), CTRL, 0xf, 0xf, true)); }
; DI void rwkv_scan_phase(int wv, const Params& P, LAS unsigned char* lds) {
;     ...
;                     if (ck + 1 < nck) { const int cn = ck + 1, buf = cn & 1;
; #pragma unroll
;                         for (int i = 0; i < 3; ++i) { const int pp = pw + 6 * i; if (pp < 16) { const int tt = 2 * pp + hf; const size_t row = (size_t)b * SEQ + cn * RW_T + tt;
;                             const f32x2 k = {bflo(gk[i]), bfhi(gk[i])}, a = {bflo(ga[i]), bfhi(ga[i])}, r = {bflo(gr[i]), bfhi(gr[i])};
;                             const h16x2 lh = __builtin_bit_cast(h16x2, gl[i]);
;                             const f32x2 kr = k * kkw2, kp = k * ((a - 1.f) * kaw2 + 1.f);
;                             const float sp = kr[0] * kr[0] + kr[1] * kr[1], rp = r[0] * kp[0] * rkw2[0] + r[1] * kp[1] * rkw2[1];
;                             const bool odd = lane & 1;
;                             float red = (odd ? rp : sp) + dpp_f<0xB1>(odd ? sp : rp);
;                             red += dpp_f<0x4E>(red); red += dpp_f<0x124>(red); red += dpp_f<0x128>(red);
;                             { auto x = __builtin_amdgcn_permlane16_swap(__float_as_uint(red), __float_as_uint(red), false, false); red = __uint_as_float(x[0]) + __uint_as_float(x[1]); }
;                             const float oth = dpp_f<0xB1>(red); const float ss = odd ? oth : red, rks = odd ? red : oth;
;                             const f32x2 kk = kr * __builtin_amdgcn_rsqf(fmaxf(ss, 1e-24f));
;                             LAS float* d = stg + ((buf * RW_T + tt) * 5) * 64 + 2 * c2;
;                             *(LAS f32x2*)(d) = -kk; *(LAS f32x2*)(d + 64) = (f32x2){__expf((float)lh[0]), __expf((float)lh[1])}; *(LAS f32x2*)(d + 128) = kk * a; *(LAS f32x2*)(d + 192) = kp; *(LAS f32x2*)(d + 256) = r;
;                             if (rg == 0 && c2 == 0) RK[row * 16 + h] = rks;
;                             if (c2 < 8) vst[(buf * RW_T + tt) * 8 + c2] = gv[i]; } }
.Lprod_stage:
	s_cmp_gt_i32 s57, 0xfe
	s_cbranch_scc1 .Lprod_flush
	s_add_i32 s67, s57, 1
	s_and_b32 s59, s67, 1
	s_mul_i32 s60, s59, 0xa000
	v_add_u32_e32 v22, s60, v2
	s_lshl_b32 s60, s59, 10
	v_add_u32_e32 v23, s60, v3
	v_lshl_add_u32 v21, v1, 3, v22
	s_lshl_b32 s66, s59, 8
	s_add_i32 s66, s66, 0x1c800
	s_lshl_b32 s60, s67, 11
	s_add_u32 s62, s50, s60
	s_addc_u32 s63, s51, 0
	s_waitcnt vmcnt(0)
	v_lshlrev_b32_e32 v64, 16, v45
	v_and_b32_e32 v65, 0xffff0000, v45
	v_pk_add_f32 v[72:73], v[64:65], -1.0 op_sel_hi:[1,0]
	v_lshlrev_b32_e32 v66, 16, v44
	v_and_b32_e32 v67, 0xffff0000, v44
	v_pk_fma_f32 v[72:73], v[6:7], v[72:73], 1.0 op_sel_hi:[1,1,0]
	v_and_b32_e32 v69, 0xffff0000, v46
	v_pk_mul_f32 v[70:71], v[4:5], v[66:67]
	v_pk_mul_f32 v[66:67], v[72:73], v[66:67]
	v_lshlrev_b32_e32 v68, 16, v46
	v_mul_f32_e32 v75, v67, v69
	v_pk_mul_f32 v[72:73], v[70:71], v[70:71]
	v_mul_f32_e32 v74, v66, v68
	v_mul_f32_e32 v75, v9, v75
	v_add_f32_e32 v76, v72, v73
	v_fmac_f32_e32 v75, v8, v74
	v_cndmask_b32_e64 v74, v75, v76, s[8:9]
	v_cndmask_b32_e64 v76, v76, v75, s[8:9]
	v_cvt_f32_f16_e32 v77, v47
	v_cvt_f32_f16_sdwa v78, v47 dst_sel:DWORD dst_unused:UNUSED_PAD src0_sel:WORD_1
	v_add_f32_dpp v76, v76, v74 quad_perm:[1,0,3,2] row_mask:0xf bank_mask:0xf bound_ctrl:1
	v_mul_f32_e32 v77, 0x3fb8aa3b, v77
	s_nop 0
	v_add_f32_dpp v76, v76, v76 quad_perm:[2,3,0,1] row_mask:0xf bank_mask:0xf bound_ctrl:1
	v_exp_f32_e32 v72, v77
	v_mul_f32_e32 v77, 0x3fb8aa3b, v78
	v_add_f32_dpp v76, v76, v76 row_ror:4 row_mask:0xf bank_mask:0xf bound_ctrl:1
	v_exp_f32_e32 v73, v77
	s_nop 0
	v_add_f32_dpp v76, v76, v76 row_ror:8 row_mask:0xf bank_mask:0xf bound_ctrl:1
	v_mov_b32_e32 v74, v76
	s_nop 1
	v_permlane16_swap_b32_e32 v76, v74
	v_add_f32_e32 v76, v76, v74
	s_nop 1
	v_mov_b32_dpp v74, v76 quad_perm:[1,0,3,2] row_mask:0xf bank_mask:0xf bound_ctrl:1
	v_cndmask_b32_e64 v75, v74, v76, s[8:9]
	v_max_f32_e32 v75, v75, v75
	v_max_f32_e32 v75, 0x179abe15, v75
	v_rsq_f32_e32 v42, v75
	v_cndmask_b32_e64 v76, v76, v74, s[8:9]
	v_lshlrev_b32_e32 v79, 16, v48
	v_pk_mul_f32 v[70:71], v[70:71], v[42:43] op_sel_hi:[1,0] neg_lo:[0,1] neg_hi:[0,1]
	ds_write_b64 v22, v[72:73] offset:512
	v_pk_mul_f32 v[64:65], v[70:71], v[64:65] neg_lo:[1,0] neg_hi:[1,0]
	ds_write_b64 v22, v[66:67] offset:1024
	v_lshl_add_u32 v77, v1, 3, s66
	ds_write_b64 v22, v[64:65] offset:768
	v_mov_b32_e32 v72, v71
	v_lshlrev_b32_e32 v71, 16, v0
	v_and_b32_e32 v73, 0xffff0000, v0
	ds_write_b128 v21, v[70:73]
	s_and_saveexec_b64 s[60:61], s[42:43]
	s_cbranch_execz .Lprod_rk_skip_0
	global_store_dword v10, v76, s[62:63]
.Lprod_rk_skip_0:
	s_mov_b64 exec, s[10:11]
	ds_write_b32 v23, v79
	s_mov_b64 exec, -1
	v_lshlrev_b32_e32 v64, 16, v50
	v_and_b32_e32 v65, 0xffff0000, v50
	v_pk_add_f32 v[72:73], v[64:65], -1.0 op_sel_hi:[1,0]
	v_lshlrev_b32_e32 v66, 16, v49
	v_and_b32_e32 v67, 0xffff0000, v49
	v_pk_fma_f32 v[72:73], v[6:7], v[72:73], 1.0 op_sel_hi:[1,1,0]
	v_and_b32_e32 v69, 0xffff0000, v51
	v_pk_mul_f32 v[70:71], v[4:5], v[66:67]
	v_pk_mul_f32 v[66:67], v[72:73], v[66:67]
	v_lshlrev_b32_e32 v68, 16, v51
	v_mul_f32_e32 v75, v67, v69
	v_pk_mul_f32 v[72:73], v[70:71], v[70:71]
	v_mul_f32_e32 v74, v66, v68
	v_mul_f32_e32 v75, v9, v75
	v_add_f32_e32 v76, v72, v73
	v_fmac_f32_e32 v75, v8, v74
	v_cndmask_b32_e64 v74, v75, v76, s[8:9]
	v_cndmask_b32_e64 v76, v76, v75, s[8:9]
	v_cvt_f32_f16_e32 v77, v52
	v_cvt_f32_f16_sdwa v78, v52 dst_sel:DWORD dst_unused:UNUSED_PAD src0_sel:WORD_1
	v_add_f32_dpp v76, v76, v74 quad_perm:[1,0,3,2] row_mask:0xf bank_mask:0xf bound_ctrl:1
	v_mul_f32_e32 v77, 0x3fb8aa3b, v77
	s_nop 0
	v_add_f32_dpp v76, v76, v76 quad_perm:[2,3,0,1] row_mask:0xf bank_mask:0xf bound_ctrl:1
	v_exp_f32_e32 v72, v77
	v_mul_f32_e32 v77, 0x3fb8aa3b, v78
	v_add_f32_dpp v76, v76, v76 row_ror:4 row_mask:0xf bank_mask:0xf bound_ctrl:1
	v_exp_f32_e32 v73, v77
	s_nop 0
	v_add_f32_dpp v76, v76, v76 row_ror:8 row_mask:0xf bank_mask:0xf bound_ctrl:1
	v_mov_b32_e32 v74, v76
	s_nop 1
	v_permlane16_swap_b32_e32 v76, v74
	v_add_f32_e32 v76, v76, v74
	s_nop 1
	v_mov_b32_dpp v74, v76 quad_perm:[1,0,3,2] row_mask:0xf bank_mask:0xf bound_ctrl:1
	v_cndmask_b32_e64 v75, v74, v76, s[8:9]
	v_max_f32_e32 v75, v75, v75
	v_max_f32_e32 v75, 0x179abe15, v75
	v_rsq_f32_e32 v42, v75
	v_cndmask_b32_e64 v76, v76, v74, s[8:9]
	v_lshlrev_b32_e32 v79, 16, v53
	v_pk_mul_f32 v[70:71], v[70:71], v[42:43] op_sel_hi:[1,0] neg_lo:[0,1] neg_hi:[0,1]
	ds_write_b64 v22, v[72:73] offset:3072
	v_pk_mul_f32 v[64:65], v[70:71], v[64:65] neg_lo:[1,0] neg_hi:[1,0]
	ds_write_b64 v22, v[66:67] offset:3584
	v_lshl_add_u32 v77, v1, 3, s66
	ds_write_b64 v22, v[64:65] offset:3328
	v_mov_b32_e32 v72, v71
	v_lshlrev_b32_e32 v71, 16, v40
	v_and_b32_e32 v73, 0xffff0000, v40
	ds_write_b128 v21, v[70:73] offset:2560
	s_and_saveexec_b64 s[60:61], s[42:43]
	s_cbranch_execz .Lprod_rk_skip_1
	global_store_dword v10, v76, s[62:63] offset:128
; #define LAS __attribute__((address_space(3)))
; DI float bflo(unsigned u) { return __uint_as_float(u << 16); }
; DI float bfhi(unsigned u) { return __uint_as_float(u & 0xffff0000u); }
; template <int CTRL> DI float dpp_f(float v) { return __builtin_bit_cast(float, __builtin_amdgcn_update_dpp(0, __builtin_bit_cast(int, v), CTRL, 0xf, 0xf, true)); }
; DI void rwkv_scan_phase(int wv, const Params& P, LAS unsigned char* lds) {
;     ...
;                     if (ck + 1 < nck) { const int cn = ck + 1, buf = cn & 1;
; #pragma unroll
;                         for (int i = 0; i < 3; ++i) { const int pp = pw + 6 * i; if (pp < 16) { const int tt = 2 * pp + hf; const size_t row = (size_t)b * SEQ + cn * RW_T + tt;
;                             const f32x2 k = {bflo(gk[i]), bfhi(gk[i])}, a = {bflo(ga[i]), bfhi(ga[i])}, r = {bflo(gr[i]), bfhi(gr[i])};
;                             const h16x2 lh = __builtin_bit_cast(h16x2, gl[i]);
;                             const f32x2 kr = k * kkw2, kp = k * ((a - 1.f) * kaw2 + 1.f);
;                             const float sp = kr[0] * kr[0] + kr[1] * kr[1], rp = r[0] * kp[0] * rkw2[0] + r[1] * kp[1] * rkw2[1];
;                             const bool odd = lane & 1;
;                             float red = (odd ? rp : sp) + dpp_f<0xB1>(odd ? sp : rp);
;                             red += dpp_f<0x4E>(red); red += dpp_f<0x124>(red); red += dpp_f<0x128>(red);
;                             { auto x = __builtin_amdgcn_permlane16_swap(__float_as_uint(red), __float_as_uint(red), false, false); red = __uint_as_float(x[0]) + __uint_as_float(x[1]); }
;                             const float oth = dpp_f<0xB1>(red); const float ss = odd ? oth : red, rks = odd ? red : oth;
;                             const f32x2 kk = kr * __builtin_amdgcn_rsqf(fmaxf(ss, 1e-24f));
;                             LAS float* d = stg + ((buf * RW_T + tt) * 5) * 64 + 2 * c2;
;                             *(LAS f32x2*)(d) = -kk; *(LAS f32x2*)(d + 64) = (f32x2){__expf((float)lh[0]), __expf((float)lh[1])}; *(LAS f32x2*)(d + 128) = kk * a; *(LAS f32x2*)(d + 192) = kp; *(LAS f32x2*)(d + 256) = r;
;                             if (rg == 0 && c2 == 0) RK[row * 16 + h] = rks;
;                             if (c2 < 8) vst[(buf * RW_T + tt) * 8 + c2] = gv[i]; } }
;                         if (ck + 2 < nck) { RW_LOADG(ck + 2) } }
.Lprod_rk_skip_1:
	s_mov_b64 exec, s[10:11]
	ds_write_b32 v23, v79 offset:64
	s_mov_b64 exec, -1
	v_lshlrev_b32_e32 v64, 16, v55
	v_and_b32_e32 v65, 0xffff0000, v55
	v_pk_add_f32 v[72:73], v[64:65], -1.0 op_sel_hi:[1,0]
	v_lshlrev_b32_e32 v66, 16, v54
	v_and_b32_e32 v67, 0xffff0000, v54
	v_pk_fma_f32 v[72:73], v[6:7], v[72:73], 1.0 op_sel_hi:[1,1,0]
	v_and_b32_e32 v69, 0xffff0000, v56
	v_pk_mul_f32 v[70:71], v[4:5], v[66:67]
	v_pk_mul_f32 v[66:67], v[72:73], v[66:67]
	v_lshlrev_b32_e32 v68, 16, v56
	v_mul_f32_e32 v75, v67, v69
	v_pk_mul_f32 v[72:73], v[70:71], v[70:71]
	v_mul_f32_e32 v74, v66, v68
	v_mul_f32_e32 v75, v9, v75
	v_add_f32_e32 v76, v72, v73
	v_fmac_f32_e32 v75, v8, v74
	v_cndmask_b32_e64 v74, v75, v76, s[8:9]
	v_cndmask_b32_e64 v76, v76, v75, s[8:9]
	v_cvt_f32_f16_e32 v77, v57
	v_cvt_f32_f16_sdwa v78, v57 dst_sel:DWORD dst_unused:UNUSED_PAD src0_sel:WORD_1
	v_add_f32_dpp v76, v76, v74 quad_perm:[1,0,3,2] row_mask:0xf bank_mask:0xf bound_ctrl:1
	v_mul_f32_e32 v77, 0x3fb8aa3b, v77
	s_nop 0
	v_add_f32_dpp v76, v76, v76 quad_perm:[2,3,0,1] row_mask:0xf bank_mask:0xf bound_ctrl:1
	v_exp_f32_e32 v72, v77
	v_mul_f32_e32 v77, 0x3fb8aa3b, v78
	v_add_f32_dpp v76, v76, v76 row_ror:4 row_mask:0xf bank_mask:0xf bound_ctrl:1
	v_exp_f32_e32 v73, v77
	s_nop 0
	v_add_f32_dpp v76, v76, v76 row_ror:8 row_mask:0xf bank_mask:0xf bound_ctrl:1
	v_mov_b32_e32 v74, v76
	s_nop 1
	v_permlane16_swap_b32_e32 v76, v74
	v_add_f32_e32 v76, v76, v74
	s_nop 1
	v_mov_b32_dpp v74, v76 quad_perm:[1,0,3,2] row_mask:0xf bank_mask:0xf bound_ctrl:1
	v_cndmask_b32_e64 v75, v74, v76, s[8:9]
	v_max_f32_e32 v75, v75, v75
	v_max_f32_e32 v75, 0x179abe15, v75
	v_rsq_f32_e32 v42, v75
	v_cndmask_b32_e64 v76, v76, v74, s[8:9]
	v_lshlrev_b32_e32 v79, 16, v58
	v_pk_mul_f32 v[70:71], v[70:71], v[42:43] op_sel_hi:[1,0] neg_lo:[0,1] neg_hi:[0,1]
	ds_write_b64 v22, v[72:73] offset:5632
	v_pk_mul_f32 v[64:65], v[70:71], v[64:65] neg_lo:[1,0] neg_hi:[1,0]
	ds_write_b64 v22, v[66:67] offset:6144
	v_lshl_add_u32 v77, v1, 3, s66
	ds_write_b64 v22, v[64:65] offset:5888
	v_mov_b32_e32 v72, v71
	v_lshlrev_b32_e32 v71, 16, v43
	v_and_b32_e32 v73, 0xffff0000, v43
	ds_write_b128 v21, v[70:73] offset:5120
	s_and_saveexec_b64 s[60:61], s[42:43]
	s_cbranch_execz .Lprod_rk_skip_2
	global_store_dword v10, v76, s[62:63] offset:256
.Lprod_rk_skip_2:
	s_mov_b64 exec, s[10:11]
	ds_write_b32 v23, v79 offset:128
	s_mov_b64 exec, -1
	v_lshlrev_b32_e32 v64, 16, v60
	v_and_b32_e32 v65, 0xffff0000, v60
	v_pk_add_f32 v[72:73], v[64:65], -1.0 op_sel_hi:[1,0]
	v_lshlrev_b32_e32 v66, 16, v59
	v_and_b32_e32 v67, 0xffff0000, v59
	v_pk_fma_f32 v[72:73], v[6:7], v[72:73], 1.0 op_sel_hi:[1,1,0]
	v_and_b32_e32 v69, 0xffff0000, v61
	v_pk_mul_f32 v[70:71], v[4:5], v[66:67]
	v_pk_mul_f32 v[66:67], v[72:73], v[66:67]
	v_lshlrev_b32_e32 v68, 16, v61
	v_mul_f32_e32 v75, v67, v69
	v_pk_mul_f32 v[72:73], v[70:71], v[70:71]
	v_mul_f32_e32 v74, v66, v68
	v_mul_f32_e32 v75, v9, v75
	v_add_f32_e32 v76, v72, v73
	v_fmac_f32_e32 v75, v8, v74
	v_cndmask_b32_e64 v74, v75, v76, s[8:9]
	v_cndmask_b32_e64 v76, v76, v75, s[8:9]
	v_cvt_f32_f16_e32 v77, v62
	v_cvt_f32_f16_sdwa v78, v62 dst_sel:DWORD dst_unused:UNUSED_PAD src0_sel:WORD_1
	v_add_f32_dpp v76, v76, v74 quad_perm:[1,0,3,2] row_mask:0xf bank_mask:0xf bound_ctrl:1
	v_mul_f32_e32 v77, 0x3fb8aa3b, v77
	s_nop 0
	v_add_f32_dpp v76, v76, v76 quad_perm:[2,3,0,1] row_mask:0xf bank_mask:0xf bound_ctrl:1
	v_exp_f32_e32 v72, v77
	v_mul_f32_e32 v77, 0x3fb8aa3b, v78
	v_add_f32_dpp v76, v76, v76 row_ror:4 row_mask:0xf bank_mask:0xf bound_ctrl:1
	v_exp_f32_e32 v73, v77
	s_nop 0
	v_add_f32_dpp v76, v76, v76 row_ror:8 row_mask:0xf bank_mask:0xf bound_ctrl:1
	v_mov_b32_e32 v74, v76
	s_nop 1
	v_permlane16_swap_b32_e32 v76, v74
	v_add_f32_e32 v76, v76, v74
	s_nop 1
	v_mov_b32_dpp v74, v76 quad_perm:[1,0,3,2] row_mask:0xf bank_mask:0xf bound_ctrl:1
	v_cndmask_b32_e64 v75, v74, v76, s[8:9]
	v_max_f32_e32 v75, v75, v75
	v_max_f32_e32 v75, 0x179abe15, v75
	v_rsq_f32_e32 v42, v75
	v_cndmask_b32_e64 v76, v76, v74, s[8:9]
	v_lshlrev_b32_e32 v79, 16, v63
	v_pk_mul_f32 v[70:71], v[70:71], v[42:43] op_sel_hi:[1,0] neg_lo:[0,1] neg_hi:[0,1]
	ds_write_b64 v22, v[72:73] offset:8192
	v_pk_mul_f32 v[64:65], v[70:71], v[64:65] neg_lo:[1,0] neg_hi:[1,0]
	ds_write_b64 v22, v[66:67] offset:8704
	v_lshl_add_u32 v77, v1, 3, s66
	ds_write_b64 v22, v[64:65] offset:8448
	v_mov_b32_e32 v72, v71
	v_lshlrev_b32_e32 v71, 16, v41
	v_and_b32_e32 v73, 0xffff0000, v41
	ds_write_b128 v21, v[70:73] offset:7680
	s_and_saveexec_b64 s[60:61], s[42:43]
	s_cbranch_execz .Lprod_rk_skip_3
	global_store_dword v10, v76, s[62:63] offset:384
.Lprod_rk_skip_3:
	s_mov_b64 exec, s[10:11]
	ds_write_b32 v23, v79 offset:192
	s_mov_b64 exec, -1
	s_cmp_lg_u32 s55, 3
	s_cbranch_scc1 .Lprod_no_r31
	s_mov_b32 exec_lo, 0
	ds_write_b64 v77, v[68:69]
	s_mov_b64 exec, -1
.Lprod_no_r31:
	s_cmp_gt_i32 s57, 0xfd
	s_cbranch_scc1 .Lprod_flush
	s_add_i32 s67, s57, 2
	s_lshl_b32 s67, s67, 16
	s_add_u32 s60, s28, s67
	s_addc_u32 s61, s29, 0
	global_load_dword v44, v12, s[60:61]
	global_load_dword v49, v13, s[60:61]
	global_load_dword v54, v14, s[60:61]
	global_load_dword v59, v15, s[60:61]
	s_add_u32 s60, s34, s67
	s_addc_u32 s61, s35, 0
	global_load_dword v45, v12, s[60:61]
	global_load_dword v50, v13, s[60:61]
	global_load_dword v55, v14, s[60:61]
	global_load_dword v60, v15, s[60:61]
	s_add_u32 s60, s22, s67
	s_addc_u32 s61, s23, 0
	global_load_dword v46, v12, s[60:61]
	global_load_dword v51, v13, s[60:61]
	global_load_dword v56, v14, s[60:61]
	global_load_dword v61, v15, s[60:61]
	s_add_u32 s60, s36, s67
	s_addc_u32 s61, s37, 0
	global_load_dword v47, v12, s[60:61]
	global_load_dword v52, v13, s[60:61]
	global_load_dword v57, v14, s[60:61]
	global_load_dword v62, v15, s[60:61]
	s_add_u32 s60, s30, s67
	s_addc_u32 s61, s31, 0
	global_load_ushort v48, v16, s[60:61]
	global_load_ushort v53, v17, s[60:61]
	global_load_ushort v58, v18, s[60:61]
	global_load_ushort v63, v19, s[60:61]
	s_add_u32 s60, s22, s67
	s_addc_u32 s61, s23, 0
	s_sub_u32 s60, s60, 0x800
	s_subb_u32 s61, s61, 0
	global_load_dword v0, v12, s[60:61]
	global_load_dword v40, v13, s[60:61]
	global_load_dword v43, v14, s[60:61]
	global_load_dword v41, v15, s[60:61]

; DI void rwkv_scan_phase(int wv, const Params& P, LAS unsigned char* lds) {
;     ...
;                         if (ck + 2 < nck) { RW_LOADG(ck + 2) } }
;                 }
;                 if (ck < nck) __syncthreads();
;             }
;         } else {
.Lprod_exit:
	v_mov_b32_e32 v41, s68
	s_branch .Lprod_done
